# all full-mode K-loops: k-innermost MFMA order + trimmed barrier rendezvous (setprio moved across barriers, redundant lgkmcnt wait dropped, loop-head SALU hoisted before barrier)
# speedup vs baseline: 1.0099x; 1.0081x over previous
.LBB0_292:
	v_mfma_i32_16x16x64_i8 v[128:131], v[148:151], v[188:191], v[128:131]
	v_mfma_i32_16x16x64_i8 v[128:131], v[152:155], v[192:195], v[128:131]
	v_mfma_i32_16x16x64_i8 v[120:123], v[156:159], v[188:191], v[120:123]
	v_mfma_i32_16x16x64_i8 v[120:123], v[160:163], v[192:195], v[120:123]
	v_mfma_i32_16x16x64_i8 v[112:115], v[148:151], v[180:183], v[112:115]
	v_mfma_i32_16x16x64_i8 v[112:115], v[152:155], v[184:187], v[112:115]
	v_mfma_i32_16x16x64_i8 v[104:107], v[156:159], v[180:183], v[104:107]
	v_mfma_i32_16x16x64_i8 v[104:107], v[160:163], v[184:187], v[104:107]
	v_mfma_i32_16x16x64_i8 v[96:99], v[148:151], v[172:175], v[96:99]
	v_mfma_i32_16x16x64_i8 v[96:99], v[152:155], v[176:179], v[96:99]
	v_mfma_i32_16x16x64_i8 v[88:91], v[156:159], v[172:175], v[88:91]
	v_mfma_i32_16x16x64_i8 v[88:91], v[160:163], v[176:179], v[88:91]
	v_mfma_i32_16x16x64_i8 v[80:83], v[148:151], v[164:167], v[80:83]
	v_mfma_i32_16x16x64_i8 v[80:83], v[152:155], v[168:171], v[80:83]
	v_mfma_i32_16x16x64_i8 v[72:75], v[156:159], v[164:167], v[72:75]
	v_mfma_i32_16x16x64_i8 v[72:75], v[160:163], v[168:171], v[72:75]
	v_mfma_i32_16x16x64_i8 v[124:127], v[132:135], v[188:191], v[124:127]
	v_mfma_i32_16x16x64_i8 v[124:127], v[136:139], v[192:195], v[124:127]
	v_mfma_i32_16x16x64_i8 v[116:119], v[140:143], v[188:191], v[116:119]
	v_mfma_i32_16x16x64_i8 v[116:119], v[144:147], v[192:195], v[116:119]
	v_mfma_i32_16x16x64_i8 v[108:111], v[132:135], v[180:183], v[108:111]
	v_mfma_i32_16x16x64_i8 v[108:111], v[136:139], v[184:187], v[108:111]
	v_mfma_i32_16x16x64_i8 v[100:103], v[140:143], v[180:183], v[100:103]
	v_mfma_i32_16x16x64_i8 v[100:103], v[144:147], v[184:187], v[100:103]
	v_mfma_i32_16x16x64_i8 v[92:95], v[132:135], v[172:175], v[92:95]
	v_mfma_i32_16x16x64_i8 v[92:95], v[136:139], v[176:179], v[92:95]
	v_mfma_i32_16x16x64_i8 v[84:87], v[140:143], v[172:175], v[84:87]
	v_mfma_i32_16x16x64_i8 v[84:87], v[144:147], v[176:179], v[84:87]
	v_mfma_i32_16x16x64_i8 v[76:79], v[132:135], v[164:167], v[76:79]
	v_mfma_i32_16x16x64_i8 v[76:79], v[136:139], v[168:171], v[76:79]
	v_mfma_i32_16x16x64_i8 v[68:71], v[140:143], v[164:167], v[68:71]
	v_mfma_i32_16x16x64_i8 v[68:71], v[144:147], v[168:171], v[68:71]
	s_barrier
	s_setprio 0
	s_mov_b32 m0, s64
	v_lshl_add_u64 v[246:247], s[36:37], 0, v[34:35]
	s_add_u32 vcc_lo, s36, 0x40000
	ds_read_b128 v[164:167], v244 offset:16384
	ds_read_b128 v[168:171], v244 offset:17408
	ds_read_b128 v[172:175], v244 offset:18432
	ds_read_b128 v[176:179], v244 offset:19456
	ds_read_b128 v[180:183], v244 offset:20480
	ds_read_b128 v[184:187], v244 offset:21504
	ds_read_b128 v[188:191], v244 offset:22528
	ds_read_b128 v[192:195], v244 offset:23552
	global_load_lds_dwordx4 v[246:247], off
	v_lshl_add_u64 v[248:249], s[36:37], 0, v[210:211]
	s_mov_b32 m0, s65
	s_addc_u32 vcc_hi, s37, 0
	global_load_lds_dwordx4 v[248:249], off
	v_lshl_add_u64 v[250:251], vcc, 0, v[34:35]
	s_mov_b32 m0, s66
	v_lshl_add_u64 v[198:199], s[42:43], 0, v[208:209]
	global_load_lds_dwordx4 v[250:251], off
	v_lshl_add_u64 v[250:251], vcc, 0, v[210:211]
	s_mov_b32 m0, s67
	s_nop 0
	global_load_lds_dwordx4 v[250:251], off
	v_lshl_add_u64 v[250:251], s[42:43], 0, v[206:207]
	s_mov_b32 m0, s63
	s_nop 0
	global_load_lds_dwordx4 v[250:251], off
	s_mov_b32 m0, s68
	s_nop 0
	global_load_lds_dwordx4 v[198:199], off
	s_waitcnt vmcnt(8)
	s_waitcnt lgkmcnt(0)
	s_setprio 1
	s_barrier
	v_mfma_i32_16x16x64_i8 v[64:67], v[148:151], v[164:167], v[64:67]
	v_mfma_i32_16x16x64_i8 v[64:67], v[152:155], v[168:171], v[64:67]
	v_mfma_i32_16x16x64_i8 v[56:59], v[156:159], v[164:167], v[56:59]
	v_mfma_i32_16x16x64_i8 v[56:59], v[160:163], v[168:171], v[56:59]
	v_mfma_i32_16x16x64_i8 v[48:51], v[148:151], v[172:175], v[48:51]
	v_mfma_i32_16x16x64_i8 v[48:51], v[152:155], v[176:179], v[48:51]
	v_mfma_i32_16x16x64_i8 v[40:43], v[156:159], v[172:175], v[40:43]
	v_mfma_i32_16x16x64_i8 v[40:43], v[160:163], v[176:179], v[40:43]
	v_mfma_i32_16x16x64_i8 v[30:33], v[148:151], v[180:183], v[30:33]
	v_mfma_i32_16x16x64_i8 v[30:33], v[152:155], v[184:187], v[30:33]
	v_mfma_i32_16x16x64_i8 v[22:25], v[156:159], v[180:183], v[22:25]
	v_mfma_i32_16x16x64_i8 v[22:25], v[160:163], v[184:187], v[22:25]
	v_mfma_i32_16x16x64_i8 v[14:17], v[148:151], v[188:191], v[14:17]
	v_mfma_i32_16x16x64_i8 v[14:17], v[152:155], v[192:195], v[14:17]
	v_mfma_i32_16x16x64_i8 v[6:9], v[156:159], v[188:191], v[6:9]
	v_mfma_i32_16x16x64_i8 v[6:9], v[160:163], v[192:195], v[6:9]
	v_mfma_i32_16x16x64_i8 v[60:63], v[132:135], v[164:167], v[60:63]
	v_mfma_i32_16x16x64_i8 v[60:63], v[136:139], v[168:171], v[60:63]
	v_mfma_i32_16x16x64_i8 v[52:55], v[140:143], v[164:167], v[52:55]
	v_mfma_i32_16x16x64_i8 v[52:55], v[144:147], v[168:171], v[52:55]
	v_mfma_i32_16x16x64_i8 v[44:47], v[132:135], v[172:175], v[44:47]
	v_mfma_i32_16x16x64_i8 v[44:47], v[136:139], v[176:179], v[44:47]
	v_mfma_i32_16x16x64_i8 v[36:39], v[140:143], v[172:175], v[36:39]
	v_mfma_i32_16x16x64_i8 v[36:39], v[144:147], v[176:179], v[36:39]
	v_mfma_i32_16x16x64_i8 v[26:29], v[132:135], v[180:183], v[26:29]
	v_mfma_i32_16x16x64_i8 v[26:29], v[136:139], v[184:187], v[26:29]
	v_mfma_i32_16x16x64_i8 v[18:21], v[140:143], v[180:183], v[18:21]
	v_mfma_i32_16x16x64_i8 v[18:21], v[144:147], v[184:187], v[18:21]
	v_mfma_i32_16x16x64_i8 v[10:13], v[132:135], v[188:191], v[10:13]
	v_mfma_i32_16x16x64_i8 v[10:13], v[136:139], v[192:195], v[10:13]
	v_mfma_i32_16x16x64_i8 v[2:5], v[140:143], v[188:191], v[2:5]
	v_mfma_i32_16x16x64_i8 v[2:5], v[144:147], v[192:195], v[2:5]
	s_barrier
	s_setprio 0
	s_add_i32 s77, 0, 0x18000
	s_add_i32 s78, 0, 0x1c000
	v_add_u32_e32 v144, s77, v243
	v_add_u32_e32 v160, s78, v243
	ds_read_b128 v[132:135], v144
	ds_read_b128 v[136:139], v144 offset:1024
	ds_read_b128 v[140:143], v144 offset:2048
	ds_read_b128 v[144:147], v144 offset:3072
	ds_read_b128 v[148:151], v160
	ds_read_b128 v[152:155], v160 offset:1024
	ds_read_b128 v[156:159], v160 offset:2048
	ds_read_b128 v[160:163], v160 offset:3072
	s_add_u32 s42, s42, 0x40000
	s_addc_u32 s43, s43, 0
	s_mov_b32 m0, s69
	v_lshl_add_u64 v[200:201], s[42:43], 0, v[206:207]
	ds_read_b128 v[164:167], v244 offset:32768
	ds_read_b128 v[168:171], v244 offset:33792
	ds_read_b128 v[172:175], v244 offset:34816
	ds_read_b128 v[176:179], v244 offset:35840
	ds_read_b128 v[180:183], v244 offset:36864
	ds_read_b128 v[184:187], v244 offset:37888
	ds_read_b128 v[188:191], v244 offset:38912
	ds_read_b128 v[192:195], v244 offset:39936
	global_load_lds_dwordx4 v[200:201], off
	v_lshl_add_u64 v[200:201], s[42:43], 0, v[208:209]
	s_mov_b32 m0, s70
	s_nop 0
	global_load_lds_dwordx4 v[200:201], off
	s_waitcnt vmcnt(8)
	s_waitcnt lgkmcnt(0)
	s_setprio 1
	s_barrier
	v_mfma_i32_16x16x64_i8 v[128:131], v[132:135], v[164:167], v[128:131]
	v_mfma_i32_16x16x64_i8 v[128:131], v[136:139], v[168:171], v[128:131]
	v_mfma_i32_16x16x64_i8 v[120:123], v[140:143], v[164:167], v[120:123]
	v_mfma_i32_16x16x64_i8 v[120:123], v[144:147], v[168:171], v[120:123]
	v_mfma_i32_16x16x64_i8 v[112:115], v[132:135], v[172:175], v[112:115]
	v_mfma_i32_16x16x64_i8 v[112:115], v[136:139], v[176:179], v[112:115]
	v_mfma_i32_16x16x64_i8 v[104:107], v[140:143], v[172:175], v[104:107]
	v_mfma_i32_16x16x64_i8 v[104:107], v[144:147], v[176:179], v[104:107]
	v_mfma_i32_16x16x64_i8 v[96:99], v[132:135], v[180:183], v[96:99]
	v_mfma_i32_16x16x64_i8 v[96:99], v[136:139], v[184:187], v[96:99]
	v_mfma_i32_16x16x64_i8 v[88:91], v[140:143], v[180:183], v[88:91]
	v_mfma_i32_16x16x64_i8 v[88:91], v[144:147], v[184:187], v[88:91]
	v_mfma_i32_16x16x64_i8 v[80:83], v[132:135], v[188:191], v[80:83]
	v_mfma_i32_16x16x64_i8 v[80:83], v[136:139], v[192:195], v[80:83]
	v_mfma_i32_16x16x64_i8 v[72:75], v[140:143], v[188:191], v[72:75]
	v_mfma_i32_16x16x64_i8 v[72:75], v[144:147], v[192:195], v[72:75]
	v_mfma_i32_16x16x64_i8 v[124:127], v[148:151], v[164:167], v[124:127]
	v_mfma_i32_16x16x64_i8 v[124:127], v[152:155], v[168:171], v[124:127]
	v_mfma_i32_16x16x64_i8 v[116:119], v[156:159], v[164:167], v[116:119]
	v_mfma_i32_16x16x64_i8 v[116:119], v[160:163], v[168:171], v[116:119]
	v_mfma_i32_16x16x64_i8 v[108:111], v[148:151], v[172:175], v[108:111]
	v_mfma_i32_16x16x64_i8 v[108:111], v[152:155], v[176:179], v[108:111]
	v_mfma_i32_16x16x64_i8 v[100:103], v[156:159], v[172:175], v[100:103]
	v_mfma_i32_16x16x64_i8 v[100:103], v[160:163], v[176:179], v[100:103]
	v_mfma_i32_16x16x64_i8 v[92:95], v[148:151], v[180:183], v[92:95]
	v_mfma_i32_16x16x64_i8 v[92:95], v[152:155], v[184:187], v[92:95]
	v_mfma_i32_16x16x64_i8 v[84:87], v[156:159], v[180:183], v[84:87]
	v_mfma_i32_16x16x64_i8 v[84:87], v[160:163], v[184:187], v[84:87]
	v_mfma_i32_16x16x64_i8 v[76:79], v[148:151], v[188:191], v[76:79]
	v_mfma_i32_16x16x64_i8 v[76:79], v[152:155], v[192:195], v[76:79]
	v_mfma_i32_16x16x64_i8 v[68:71], v[156:159], v[188:191], v[68:71]
	v_mfma_i32_16x16x64_i8 v[68:71], v[160:163], v[192:195], v[68:71]
	s_barrier
	s_setprio 0
	s_add_i32 s42, s77, s62
	v_lshl_add_u64 v[200:201], v[246:247], 0, s[18:19]
	s_mov_b32 m0, s42
	ds_read_b128 v[164:167], v244 offset:49152
	ds_read_b128 v[168:171], v244 offset:50176
	ds_read_b128 v[172:175], v244 offset:51200
	ds_read_b128 v[176:179], v244 offset:52224
	ds_read_b128 v[180:183], v244 offset:53248
	ds_read_b128 v[184:187], v244 offset:54272
	ds_read_b128 v[188:191], v244 offset:55296
	ds_read_b128 v[192:195], v244 offset:56320
	global_load_lds_dwordx4 v[200:201], off
	s_add_i32 m0, s42, 0x2000
	s_add_u32 s36, s36, 0x40080
	v_lshl_add_u64 v[200:201], v[248:249], 0, s[18:19]
	s_addc_u32 s37, s37, 0
	s_add_i32 s42, s78, s62
	global_load_lds_dwordx4 v[200:201], off
	v_lshl_add_u64 v[200:201], s[36:37], 0, v[34:35]
	s_mov_b32 m0, s42
	v_lshl_add_u64 v[198:199], v[198:199], 0, s[18:19]
	global_load_lds_dwordx4 v[200:201], off
	v_lshl_add_u64 v[200:201], s[36:37], 0, v[210:211]
	s_add_i32 m0, s42, 0x2000
	s_nop 0
	global_load_lds_dwordx4 v[200:201], off
	v_lshl_add_u64 v[200:201], v[250:251], 0, s[18:19]
	s_mov_b32 m0, s71
	s_nop 0
	global_load_lds_dwordx4 v[200:201], off
	s_mov_b32 m0, s72
	s_nop 0
	global_load_lds_dwordx4 v[198:199], off
	s_waitcnt vmcnt(8)
	s_waitcnt lgkmcnt(0)
	s_setprio 1
	s_barrier
	v_mfma_i32_16x16x64_i8 v[64:67], v[132:135], v[164:167], v[64:67]
	v_mfma_i32_16x16x64_i8 v[64:67], v[136:139], v[168:171], v[64:67]
	v_mfma_i32_16x16x64_i8 v[56:59], v[140:143], v[164:167], v[56:59]
	v_mfma_i32_16x16x64_i8 v[56:59], v[144:147], v[168:171], v[56:59]
	v_mfma_i32_16x16x64_i8 v[48:51], v[132:135], v[172:175], v[48:51]
	v_mfma_i32_16x16x64_i8 v[48:51], v[136:139], v[176:179], v[48:51]
	v_mfma_i32_16x16x64_i8 v[40:43], v[140:143], v[172:175], v[40:43]
	v_mfma_i32_16x16x64_i8 v[40:43], v[144:147], v[176:179], v[40:43]
	v_mfma_i32_16x16x64_i8 v[30:33], v[132:135], v[180:183], v[30:33]
	v_mfma_i32_16x16x64_i8 v[30:33], v[136:139], v[184:187], v[30:33]
	v_mfma_i32_16x16x64_i8 v[22:25], v[140:143], v[180:183], v[22:25]
	v_mfma_i32_16x16x64_i8 v[22:25], v[144:147], v[184:187], v[22:25]
	v_mfma_i32_16x16x64_i8 v[14:17], v[132:135], v[188:191], v[14:17]
	v_mfma_i32_16x16x64_i8 v[14:17], v[136:139], v[192:195], v[14:17]
	v_mfma_i32_16x16x64_i8 v[6:9], v[140:143], v[188:191], v[6:9]
	v_mfma_i32_16x16x64_i8 v[6:9], v[144:147], v[192:195], v[6:9]
	v_mfma_i32_16x16x64_i8 v[60:63], v[148:151], v[164:167], v[60:63]
	v_mfma_i32_16x16x64_i8 v[60:63], v[152:155], v[168:171], v[60:63]
	v_mfma_i32_16x16x64_i8 v[52:55], v[156:159], v[164:167], v[52:55]
	v_mfma_i32_16x16x64_i8 v[52:55], v[160:163], v[168:171], v[52:55]
	v_mfma_i32_16x16x64_i8 v[44:47], v[148:151], v[172:175], v[44:47]
	v_mfma_i32_16x16x64_i8 v[44:47], v[152:155], v[176:179], v[44:47]
	v_mfma_i32_16x16x64_i8 v[36:39], v[156:159], v[172:175], v[36:39]
	v_mfma_i32_16x16x64_i8 v[36:39], v[160:163], v[176:179], v[36:39]
	v_mfma_i32_16x16x64_i8 v[26:29], v[148:151], v[180:183], v[26:29]
	v_mfma_i32_16x16x64_i8 v[26:29], v[152:155], v[184:187], v[26:29]
	v_mfma_i32_16x16x64_i8 v[18:21], v[156:159], v[180:183], v[18:21]
	v_mfma_i32_16x16x64_i8 v[18:21], v[160:163], v[184:187], v[18:21]
	v_mfma_i32_16x16x64_i8 v[10:13], v[148:151], v[188:191], v[10:13]
	v_mfma_i32_16x16x64_i8 v[10:13], v[152:155], v[192:195], v[10:13]
	v_mfma_i32_16x16x64_i8 v[2:5], v[156:159], v[188:191], v[2:5]
	v_mfma_i32_16x16x64_i8 v[2:5], v[160:163], v[192:195], v[2:5]
	s_barrier
	s_setprio 0
	s_add_i32 s76, s76, 2
	s_add_u32 s34, s34, 0x100
	s_addc_u32 s35, s35, 0
	s_cmp_gt_u32 s76, 13
	s_cbranch_scc1 .LBB0_295
.LBB0_293:
	v_add_u32_e32 v132, 0, v243
	v_add_u32_e32 v133, 0x10000, v132
	v_add_u32_e32 v144, 0x14000, v132
	ds_read_b128 v[148:151], v133
	ds_read_b128 v[152:155], v133 offset:1024
	ds_read_b128 v[156:159], v133 offset:2048
	ds_read_b128 v[160:163], v133 offset:3072
	ds_read_b128 v[132:135], v144
	ds_read_b128 v[136:139], v144 offset:1024
	ds_read_b128 v[140:143], v144 offset:2048
	ds_read_b128 v[144:147], v144 offset:3072
	v_lshl_add_u64 v[246:247], v[224:225], 0, s[34:35]
	s_add_i32 m0, s63, 0xc000
	ds_read_b128 v[188:191], v244
	ds_read_b128 v[192:195], v244 offset:1024
	ds_read_b128 v[180:183], v244 offset:2048
	ds_read_b128 v[184:187], v244 offset:3072
	ds_read_b128 v[172:175], v244 offset:4096
	ds_read_b128 v[176:179], v244 offset:5120
	ds_read_b128 v[164:167], v244 offset:6144
	ds_read_b128 v[168:171], v244 offset:7168
	global_load_lds_dwordx4 v[246:247], off
	v_lshl_add_u64 v[246:247], v[226:227], 0, s[34:35]
	s_add_i32 m0, s63, 0xe000
	s_cmp_eq_u32 s34, 0
	global_load_lds_dwordx4 v[246:247], off
	s_waitcnt vmcnt(8)
	s_waitcnt lgkmcnt(0)
	s_cselect_b64 s[36:37], -1, 0
	s_and_b64 s[36:37], s[36:37], s[12:13]
	s_andn2_b64 vcc, exec, s[36:37]
	s_add_u32 s36, s28, s34
	s_addc_u32 s37, s29, s35
	s_add_u32 s36, s36, 0x100
	s_addc_u32 s37, s37, 0
	s_add_u32 s77, s27, s34
	s_addc_u32 s78, s31, s35
	s_cmpk_eq_i32 s34, 0x700
	s_cselect_b32 s43, s21, s37
	s_cselect_b32 s42, s74, s36
	s_cselect_b32 s37, s17, s78
	s_cselect_b32 s36, s75, s77
	s_setprio 1
	s_barrier
	s_cbranch_vccnz .LBB0_292
	s_add_i32 m0, s63, 0x21200
	s_nop 0
	global_load_lds_dwordx4 v[222:223], off
	s_branch .LBB0_292

.LBB0_462:
	s_add_u32 s24, s26, 0x100
	s_addc_u32 s25, s27, 0
	s_add_i32 s43, 0, 0x10000
	s_cmp_eq_u32 s42, 40
	s_cselect_b32 s31, s21, s25
	s_cselect_b32 s30, s20, s24
	s_cselect_b32 s29, s23, s13
	s_cselect_b32 s28, s22, s11
	s_add_i32 s60, 0, 0x14000
	v_add_u32_e32 v2, s43, v187
	v_add_u32_e32 v14, s60, v187
	ds_read_b128 v[18:21], v2
	ds_read_b128 v[22:25], v2 offset:1024
	ds_read_b128 v[26:29], v2 offset:2048
	ds_read_b128 v[30:33], v2 offset:3072
	ds_read_b128 v[2:5], v14
	ds_read_b128 v[6:9], v14 offset:1024
	ds_read_b128 v[10:13], v14 offset:2048
	ds_read_b128 v[14:17], v14 offset:3072
	v_lshl_add_u64 v[182:183], s[26:27], 0, v[170:171]
	s_add_i32 m0, s39, 0xc000
	ds_read_b128 v[174:177], v188
	ds_read_b128 v[178:181], v188 offset:1024
	ds_read_b128 v[190:193], v188 offset:2048
	ds_read_b128 v[194:197], v188 offset:3072
	ds_read_b128 v[206:209], v188 offset:4096
	ds_read_b128 v[210:213], v188 offset:5120
	ds_read_b128 v[214:217], v188 offset:6144
	ds_read_b128 v[218:221], v188 offset:7168
	global_load_lds_dwordx4 v[182:183], off
	v_lshl_add_u64 v[182:183], s[26:27], 0, v[172:173]
	s_add_i32 m0, s39, 0xe000
	s_nop 0
	global_load_lds_dwordx4 v[182:183], off
	s_waitcnt vmcnt(8)
	s_waitcnt lgkmcnt(0)
	s_setprio 1
	s_barrier
	v_mfma_scale_f32_16x16x128_f8f6f4 v[160:163], v[18:25], v[174:181], v[160:163], v186, v186 op_sel_hi:[0,0,0]
	v_mfma_scale_f32_16x16x128_f8f6f4 v[156:159], v[26:33], v[174:181], v[156:159], v186, v186 op_sel_hi:[0,0,0]
	v_mfma_scale_f32_16x16x128_f8f6f4 v[144:147], v[18:25], v[190:197], v[144:147], v186, v186 op_sel_hi:[0,0,0]
	v_mfma_scale_f32_16x16x128_f8f6f4 v[140:143], v[26:33], v[190:197], v[140:143], v186, v186 op_sel_hi:[0,0,0]
	v_mfma_scale_f32_16x16x128_f8f6f4 v[128:131], v[18:25], v[206:213], v[128:131], v186, v186 op_sel_hi:[0,0,0]
	v_mfma_scale_f32_16x16x128_f8f6f4 v[124:127], v[26:33], v[206:213], v[124:127], v186, v186 op_sel_hi:[0,0,0]
	v_mfma_scale_f32_16x16x128_f8f6f4 v[112:115], v[18:25], v[214:221], v[112:115], v186, v186 op_sel_hi:[0,0,0]
	v_mfma_scale_f32_16x16x128_f8f6f4 v[108:111], v[26:33], v[214:221], v[108:111], v186, v186 op_sel_hi:[0,0,0]
	v_mfma_scale_f32_16x16x128_f8f6f4 v[152:155], v[2:9], v[174:181], v[152:155], v186, v186 op_sel_hi:[0,0,0]
	v_mfma_scale_f32_16x16x128_f8f6f4 v[148:151], v[10:17], v[174:181], v[148:151], v186, v186 op_sel_hi:[0,0,0]
	v_mfma_scale_f32_16x16x128_f8f6f4 v[136:139], v[2:9], v[190:197], v[136:139], v186, v186 op_sel_hi:[0,0,0]
	v_mfma_scale_f32_16x16x128_f8f6f4 v[132:135], v[10:17], v[190:197], v[132:135], v186, v186 op_sel_hi:[0,0,0]
	v_mfma_scale_f32_16x16x128_f8f6f4 v[120:123], v[2:9], v[206:213], v[120:123], v186, v186 op_sel_hi:[0,0,0]
	v_mfma_scale_f32_16x16x128_f8f6f4 v[116:119], v[10:17], v[206:213], v[116:119], v186, v186 op_sel_hi:[0,0,0]
	v_mfma_scale_f32_16x16x128_f8f6f4 v[104:107], v[2:9], v[214:221], v[104:107], v186, v186 op_sel_hi:[0,0,0]
	v_mfma_scale_f32_16x16x128_f8f6f4 v[100:103], v[10:17], v[214:221], v[100:103], v186, v186 op_sel_hi:[0,0,0]
	s_barrier
	s_setprio 0
	s_add_i32 s26, s43, s38
	v_lshl_add_u64 v[174:175], s[28:29], 0, v[34:35]
	s_mov_b32 m0, s26
	ds_read_b128 v[190:193], v188 offset:16384
	ds_read_b128 v[194:197], v188 offset:17408
	ds_read_b128 v[206:209], v188 offset:18432
	ds_read_b128 v[210:213], v188 offset:19456
	ds_read_b128 v[214:217], v188 offset:20480
	ds_read_b128 v[218:221], v188 offset:21504
	ds_read_b128 v[240:243], v188 offset:22528
	ds_read_b128 v[244:247], v188 offset:23552
	global_load_lds_dwordx4 v[174:175], off
	s_add_i32 m0, s26, 0x2000
	s_add_u32 s26, s28, 0xb0000
	v_lshl_add_u64 v[176:177], s[28:29], 0, v[168:169]
	s_addc_u32 s27, s29, 0
	s_add_i32 s43, s60, s38
	global_load_lds_dwordx4 v[176:177], off
	v_lshl_add_u64 v[178:179], s[26:27], 0, v[34:35]
	s_mov_b32 m0, s43
	v_lshl_add_u64 v[180:181], s[30:31], 0, v[166:167]
	global_load_lds_dwordx4 v[178:179], off
	v_lshl_add_u64 v[178:179], s[26:27], 0, v[168:169]
	s_add_i32 m0, s43, 0x2000
	s_nop 0
	global_load_lds_dwordx4 v[178:179], off
	v_lshl_add_u64 v[178:179], s[30:31], 0, v[164:165]
	s_mov_b32 m0, s39
	s_nop 0
	global_load_lds_dwordx4 v[178:179], off
	s_mov_b32 m0, s44
	s_nop 0
	global_load_lds_dwordx4 v[180:181], off
	s_waitcnt vmcnt(8)
	s_waitcnt lgkmcnt(0)
	s_setprio 1
	s_barrier
	v_mfma_scale_f32_16x16x128_f8f6f4 v[96:99], v[18:25], v[190:197], v[96:99], v186, v186 op_sel_hi:[0,0,0]
	v_mfma_scale_f32_16x16x128_f8f6f4 v[92:95], v[26:33], v[190:197], v[92:95], v186, v186 op_sel_hi:[0,0,0]
	v_mfma_scale_f32_16x16x128_f8f6f4 v[80:83], v[18:25], v[206:213], v[80:83], v186, v186 op_sel_hi:[0,0,0]
	v_mfma_scale_f32_16x16x128_f8f6f4 v[76:79], v[26:33], v[206:213], v[76:79], v186, v186 op_sel_hi:[0,0,0]
	v_mfma_scale_f32_16x16x128_f8f6f4 v[64:67], v[18:25], v[214:221], v[64:67], v186, v186 op_sel_hi:[0,0,0]
	v_mfma_scale_f32_16x16x128_f8f6f4 v[60:63], v[26:33], v[214:221], v[60:63], v186, v186 op_sel_hi:[0,0,0]
	v_mfma_scale_f32_16x16x128_f8f6f4 v[48:51], v[18:25], v[240:247], v[48:51], v186, v186 op_sel_hi:[0,0,0]
	v_mfma_scale_f32_16x16x128_f8f6f4 v[44:47], v[26:33], v[240:247], v[44:47], v186, v186 op_sel_hi:[0,0,0]
	v_mfma_scale_f32_16x16x128_f8f6f4 v[88:91], v[2:9], v[190:197], v[88:91], v186, v186 op_sel_hi:[0,0,0]
	v_mfma_scale_f32_16x16x128_f8f6f4 v[84:87], v[10:17], v[190:197], v[84:87], v186, v186 op_sel_hi:[0,0,0]
	v_mfma_scale_f32_16x16x128_f8f6f4 v[72:75], v[2:9], v[206:213], v[72:75], v186, v186 op_sel_hi:[0,0,0]
	v_mfma_scale_f32_16x16x128_f8f6f4 v[68:71], v[10:17], v[206:213], v[68:71], v186, v186 op_sel_hi:[0,0,0]
	v_mfma_scale_f32_16x16x128_f8f6f4 v[56:59], v[2:9], v[214:221], v[56:59], v186, v186 op_sel_hi:[0,0,0]
	v_mfma_scale_f32_16x16x128_f8f6f4 v[52:55], v[10:17], v[214:221], v[52:55], v186, v186 op_sel_hi:[0,0,0]
	v_mfma_scale_f32_16x16x128_f8f6f4 v[40:43], v[2:9], v[240:247], v[40:43], v186, v186 op_sel_hi:[0,0,0]
	v_mfma_scale_f32_16x16x128_f8f6f4 v[36:39], v[10:17], v[240:247], v[36:39], v186, v186 op_sel_hi:[0,0,0]
	s_barrier
	s_setprio 0
	s_add_i32 s43, 0, 0x18000
	s_add_i32 s60, 0, 0x1c000
	v_add_u32_e32 v14, s43, v187
	v_add_u32_e32 v30, s60, v187
	ds_read_b128 v[2:5], v14
	ds_read_b128 v[6:9], v14 offset:1024
	ds_read_b128 v[10:13], v14 offset:2048
	ds_read_b128 v[14:17], v14 offset:3072
	ds_read_b128 v[18:21], v30
	ds_read_b128 v[22:25], v30 offset:1024
	ds_read_b128 v[26:29], v30 offset:2048
	ds_read_b128 v[30:33], v30 offset:3072
	s_add_u32 s26, s30, 0xb0000
	s_addc_u32 s27, s31, 0
	s_mov_b32 m0, s45
	v_lshl_add_u64 v[182:183], s[26:27], 0, v[164:165]
	ds_read_b128 v[190:193], v188 offset:32768
	ds_read_b128 v[194:197], v188 offset:33792
	ds_read_b128 v[206:209], v188 offset:34816
	ds_read_b128 v[210:213], v188 offset:35840
	ds_read_b128 v[214:217], v188 offset:36864
	ds_read_b128 v[218:221], v188 offset:37888
	ds_read_b128 v[240:243], v188 offset:38912
	ds_read_b128 v[244:247], v188 offset:39936
	global_load_lds_dwordx4 v[182:183], off
	v_lshl_add_u64 v[182:183], s[26:27], 0, v[166:167]
	s_mov_b32 m0, s46
	s_nop 0
	global_load_lds_dwordx4 v[182:183], off
	s_waitcnt vmcnt(8)
	s_waitcnt lgkmcnt(0)
	s_setprio 1
	s_barrier
	v_mfma_scale_f32_16x16x128_f8f6f4 v[160:163], v[2:9], v[190:197], v[160:163], v186, v186 op_sel_hi:[0,0,0]
	v_mfma_scale_f32_16x16x128_f8f6f4 v[156:159], v[10:17], v[190:197], v[156:159], v186, v186 op_sel_hi:[0,0,0]
	v_mfma_scale_f32_16x16x128_f8f6f4 v[144:147], v[2:9], v[206:213], v[144:147], v186, v186 op_sel_hi:[0,0,0]
	v_mfma_scale_f32_16x16x128_f8f6f4 v[140:143], v[10:17], v[206:213], v[140:143], v186, v186 op_sel_hi:[0,0,0]
	v_mfma_scale_f32_16x16x128_f8f6f4 v[128:131], v[2:9], v[214:221], v[128:131], v186, v186 op_sel_hi:[0,0,0]
	v_mfma_scale_f32_16x16x128_f8f6f4 v[124:127], v[10:17], v[214:221], v[124:127], v186, v186 op_sel_hi:[0,0,0]
	v_mfma_scale_f32_16x16x128_f8f6f4 v[112:115], v[2:9], v[240:247], v[112:115], v186, v186 op_sel_hi:[0,0,0]
	v_mfma_scale_f32_16x16x128_f8f6f4 v[108:111], v[10:17], v[240:247], v[108:111], v186, v186 op_sel_hi:[0,0,0]
	v_mfma_scale_f32_16x16x128_f8f6f4 v[152:155], v[18:25], v[190:197], v[152:155], v186, v186 op_sel_hi:[0,0,0]
	v_mfma_scale_f32_16x16x128_f8f6f4 v[148:151], v[26:33], v[190:197], v[148:151], v186, v186 op_sel_hi:[0,0,0]
	v_mfma_scale_f32_16x16x128_f8f6f4 v[136:139], v[18:25], v[206:213], v[136:139], v186, v186 op_sel_hi:[0,0,0]
	v_mfma_scale_f32_16x16x128_f8f6f4 v[132:135], v[26:33], v[206:213], v[132:135], v186, v186 op_sel_hi:[0,0,0]
	v_mfma_scale_f32_16x16x128_f8f6f4 v[120:123], v[18:25], v[214:221], v[120:123], v186, v186 op_sel_hi:[0,0,0]
	v_mfma_scale_f32_16x16x128_f8f6f4 v[116:119], v[26:33], v[214:221], v[116:119], v186, v186 op_sel_hi:[0,0,0]
	v_mfma_scale_f32_16x16x128_f8f6f4 v[104:107], v[18:25], v[240:247], v[104:107], v186, v186 op_sel_hi:[0,0,0]
	v_mfma_scale_f32_16x16x128_f8f6f4 v[100:103], v[26:33], v[240:247], v[100:103], v186, v186 op_sel_hi:[0,0,0]
	s_barrier
	s_setprio 0
	s_add_i32 s26, s43, s38
	v_lshl_add_u64 v[174:175], v[174:175], 0, s[18:19]
	s_mov_b32 m0, s26
	ds_read_b128 v[190:193], v188 offset:49152
	ds_read_b128 v[194:197], v188 offset:50176
	ds_read_b128 v[206:209], v188 offset:51200
	ds_read_b128 v[210:213], v188 offset:52224
	ds_read_b128 v[214:217], v188 offset:53248
	ds_read_b128 v[218:221], v188 offset:54272
	ds_read_b128 v[240:243], v188 offset:55296
	ds_read_b128 v[244:247], v188 offset:56320
	global_load_lds_dwordx4 v[174:175], off
	s_add_i32 m0, s26, 0x2000
	s_add_u32 s26, s28, 0xb0080
	v_lshl_add_u64 v[174:175], v[176:177], 0, s[18:19]
	s_addc_u32 s27, s29, 0
	s_add_i32 s28, s60, s38
	global_load_lds_dwordx4 v[174:175], off
	v_lshl_add_u64 v[174:175], s[26:27], 0, v[34:35]
	s_mov_b32 m0, s28
	s_nop 0
	global_load_lds_dwordx4 v[174:175], off
	v_lshl_add_u64 v[174:175], s[26:27], 0, v[168:169]
	s_add_i32 m0, s28, 0x2000
	s_nop 0
	global_load_lds_dwordx4 v[174:175], off
	v_lshl_add_u64 v[174:175], v[178:179], 0, s[18:19]
	s_mov_b32 m0, s47
	s_nop 0
	global_load_lds_dwordx4 v[174:175], off
	v_lshl_add_u64 v[174:175], v[180:181], 0, s[18:19]
	s_mov_b32 m0, s52
	s_nop 0
	global_load_lds_dwordx4 v[174:175], off
	s_waitcnt vmcnt(8)
	s_waitcnt lgkmcnt(0)
	s_setprio 1
	s_barrier
	v_mfma_scale_f32_16x16x128_f8f6f4 v[96:99], v[2:9], v[190:197], v[96:99], v186, v186 op_sel_hi:[0,0,0]
	v_mfma_scale_f32_16x16x128_f8f6f4 v[92:95], v[10:17], v[190:197], v[92:95], v186, v186 op_sel_hi:[0,0,0]
	v_mfma_scale_f32_16x16x128_f8f6f4 v[80:83], v[2:9], v[206:213], v[80:83], v186, v186 op_sel_hi:[0,0,0]
	v_mfma_scale_f32_16x16x128_f8f6f4 v[76:79], v[10:17], v[206:213], v[76:79], v186, v186 op_sel_hi:[0,0,0]
	v_mfma_scale_f32_16x16x128_f8f6f4 v[64:67], v[2:9], v[214:221], v[64:67], v186, v186 op_sel_hi:[0,0,0]
	v_mfma_scale_f32_16x16x128_f8f6f4 v[60:63], v[10:17], v[214:221], v[60:63], v186, v186 op_sel_hi:[0,0,0]
	v_mfma_scale_f32_16x16x128_f8f6f4 v[48:51], v[2:9], v[240:247], v[48:51], v186, v186 op_sel_hi:[0,0,0]
	v_mfma_scale_f32_16x16x128_f8f6f4 v[44:47], v[10:17], v[240:247], v[44:47], v186, v186 op_sel_hi:[0,0,0]
	v_mfma_scale_f32_16x16x128_f8f6f4 v[88:91], v[18:25], v[190:197], v[88:91], v186, v186 op_sel_hi:[0,0,0]
	v_mfma_scale_f32_16x16x128_f8f6f4 v[84:87], v[26:33], v[190:197], v[84:87], v186, v186 op_sel_hi:[0,0,0]
	v_mfma_scale_f32_16x16x128_f8f6f4 v[72:75], v[18:25], v[206:213], v[72:75], v186, v186 op_sel_hi:[0,0,0]
	v_mfma_scale_f32_16x16x128_f8f6f4 v[68:71], v[26:33], v[206:213], v[68:71], v186, v186 op_sel_hi:[0,0,0]
	v_mfma_scale_f32_16x16x128_f8f6f4 v[56:59], v[18:25], v[214:221], v[56:59], v186, v186 op_sel_hi:[0,0,0]
	v_mfma_scale_f32_16x16x128_f8f6f4 v[52:55], v[26:33], v[214:221], v[52:55], v186, v186 op_sel_hi:[0,0,0]
	v_mfma_scale_f32_16x16x128_f8f6f4 v[40:43], v[18:25], v[240:247], v[40:43], v186, v186 op_sel_hi:[0,0,0]
	v_mfma_scale_f32_16x16x128_f8f6f4 v[36:39], v[26:33], v[240:247], v[36:39], v186, v186 op_sel_hi:[0,0,0]
	s_barrier
	s_setprio 0
	s_add_i32 s42, s42, 2
	s_add_u32 s11, s11, 0x100
	s_addc_u32 s13, s13, 0
	s_cmp_gt_u32 s42, 41
	s_mov_b64 s[26:27], s[24:25]
	s_cbranch_scc0 .LBB0_462
	s_and_b64 vcc, exec, s[16:17]
	s_cbranch_vccz .LBB0_465
	s_barrier

.LBB0_546:
	s_add_u32 s26, s24, 0x100
	s_addc_u32 s27, s25, 0
	s_add_i32 s43, 0, 0x10000
	s_cmpk_eq_i32 s42, 0x54
	s_cselect_b32 s31, s21, s27
	s_cselect_b32 s30, s20, s26
	s_cselect_b32 s29, s23, s13
	s_cselect_b32 s28, s22, s11
	s_add_i32 s60, 0, 0x14000
	v_add_u32_e32 v144, s43, v186
	v_add_u32_e32 v170, s60, v186
	ds_read_b128 v[132:135], v144
	ds_read_b128 v[136:139], v144 offset:1024
	ds_read_b128 v[140:143], v144 offset:2048
	ds_read_b128 v[144:147], v144 offset:3072
	ds_read_b128 v[148:151], v170
	ds_read_b128 v[152:155], v170 offset:1024
	ds_read_b128 v[156:159], v170 offset:2048
	ds_read_b128 v[170:173], v170 offset:3072
	v_lshl_add_u64 v[182:183], s[24:25], 0, v[166:167]
	s_add_i32 m0, s39, 0xc000
	ds_read_b128 v[174:177], v187
	ds_read_b128 v[178:181], v187 offset:1024
	ds_read_b128 v[188:191], v187 offset:2048
	ds_read_b128 v[192:195], v187 offset:3072
	ds_read_b128 v[206:209], v187 offset:4096
	ds_read_b128 v[210:213], v187 offset:5120
	ds_read_b128 v[214:217], v187 offset:6144
	ds_read_b128 v[218:221], v187 offset:7168
	global_load_lds_dwordx4 v[182:183], off
	v_lshl_add_u64 v[182:183], s[24:25], 0, v[168:169]
	s_add_i32 m0, s39, 0xe000
	s_nop 0
	global_load_lds_dwordx4 v[182:183], off
	s_waitcnt vmcnt(8)
	s_waitcnt lgkmcnt(0)
	s_setprio 1
	s_barrier
	v_mfma_f32_16x16x32_bf16 v[128:131], v[132:135], v[174:177], v[128:131]
	v_mfma_f32_16x16x32_bf16 v[128:131], v[136:139], v[178:181], v[128:131]
	v_mfma_f32_16x16x32_bf16 v[124:127], v[140:143], v[174:177], v[124:127]
	v_mfma_f32_16x16x32_bf16 v[124:127], v[144:147], v[178:181], v[124:127]
	v_mfma_f32_16x16x32_bf16 v[112:115], v[132:135], v[188:191], v[112:115]
	v_mfma_f32_16x16x32_bf16 v[112:115], v[136:139], v[192:195], v[112:115]
	v_mfma_f32_16x16x32_bf16 v[108:111], v[140:143], v[188:191], v[108:111]
	v_mfma_f32_16x16x32_bf16 v[108:111], v[144:147], v[192:195], v[108:111]
	v_mfma_f32_16x16x32_bf16 v[96:99], v[132:135], v[206:209], v[96:99]
	v_mfma_f32_16x16x32_bf16 v[96:99], v[136:139], v[210:213], v[96:99]
	v_mfma_f32_16x16x32_bf16 v[92:95], v[140:143], v[206:209], v[92:95]
	v_mfma_f32_16x16x32_bf16 v[92:95], v[144:147], v[210:213], v[92:95]
	v_mfma_f32_16x16x32_bf16 v[80:83], v[132:135], v[214:217], v[80:83]
	v_mfma_f32_16x16x32_bf16 v[80:83], v[136:139], v[218:221], v[80:83]
	v_mfma_f32_16x16x32_bf16 v[76:79], v[140:143], v[214:217], v[76:79]
	v_mfma_f32_16x16x32_bf16 v[76:79], v[144:147], v[218:221], v[76:79]
	v_mfma_f32_16x16x32_bf16 v[120:123], v[148:151], v[174:177], v[120:123]
	v_mfma_f32_16x16x32_bf16 v[120:123], v[152:155], v[178:181], v[120:123]
	v_mfma_f32_16x16x32_bf16 v[116:119], v[156:159], v[174:177], v[116:119]
	v_mfma_f32_16x16x32_bf16 v[116:119], v[170:173], v[178:181], v[116:119]
	v_mfma_f32_16x16x32_bf16 v[104:107], v[148:151], v[188:191], v[104:107]
	v_mfma_f32_16x16x32_bf16 v[104:107], v[152:155], v[192:195], v[104:107]
	v_mfma_f32_16x16x32_bf16 v[100:103], v[156:159], v[188:191], v[100:103]
	v_mfma_f32_16x16x32_bf16 v[100:103], v[170:173], v[192:195], v[100:103]
	v_mfma_f32_16x16x32_bf16 v[88:91], v[148:151], v[206:209], v[88:91]
	v_mfma_f32_16x16x32_bf16 v[88:91], v[152:155], v[210:213], v[88:91]
	v_mfma_f32_16x16x32_bf16 v[84:87], v[156:159], v[206:209], v[84:87]
	v_mfma_f32_16x16x32_bf16 v[84:87], v[170:173], v[210:213], v[84:87]
	v_mfma_f32_16x16x32_bf16 v[72:75], v[148:151], v[214:217], v[72:75]
	v_mfma_f32_16x16x32_bf16 v[72:75], v[152:155], v[218:221], v[72:75]
	v_mfma_f32_16x16x32_bf16 v[68:71], v[156:159], v[214:217], v[68:71]
	v_mfma_f32_16x16x32_bf16 v[68:71], v[170:173], v[218:221], v[68:71]
	s_barrier
	s_setprio 0
	s_add_i32 s24, s43, s38
	v_lshl_add_u64 v[182:183], s[28:29], 0, v[34:35]
	s_mov_b32 m0, s24
	ds_read_b128 v[174:177], v187 offset:16384
	ds_read_b128 v[178:181], v187 offset:17408
	ds_read_b128 v[188:191], v187 offset:18432
	ds_read_b128 v[192:195], v187 offset:19456
	ds_read_b128 v[206:209], v187 offset:20480
	ds_read_b128 v[210:213], v187 offset:21504
	ds_read_b128 v[214:217], v187 offset:22528
	ds_read_b128 v[218:221], v187 offset:23552
	global_load_lds_dwordx4 v[182:183], off
	s_add_i32 m0, s24, 0x2000
	s_add_u32 s24, s28, 0x160000
	v_lshl_add_u64 v[196:197], s[28:29], 0, v[164:165]
	s_addc_u32 s25, s29, 0
	s_add_i32 s43, s60, s38
	global_load_lds_dwordx4 v[196:197], off
	v_lshl_add_u64 v[198:199], s[24:25], 0, v[34:35]
	s_mov_b32 m0, s43
	v_lshl_add_u64 v[200:201], s[30:31], 0, v[162:163]
	global_load_lds_dwordx4 v[198:199], off
	v_lshl_add_u64 v[198:199], s[24:25], 0, v[164:165]
	s_add_i32 m0, s43, 0x2000
	s_nop 0
	global_load_lds_dwordx4 v[198:199], off
	v_lshl_add_u64 v[198:199], s[30:31], 0, v[160:161]
	s_mov_b32 m0, s39
	s_nop 0
	global_load_lds_dwordx4 v[198:199], off
	s_mov_b32 m0, s44
	s_nop 0
	global_load_lds_dwordx4 v[200:201], off
	s_waitcnt vmcnt(8)
	s_waitcnt lgkmcnt(0)
	s_setprio 1
	s_barrier
	v_mfma_f32_16x16x32_bf16 v[64:67], v[132:135], v[174:177], v[64:67]
	v_mfma_f32_16x16x32_bf16 v[64:67], v[136:139], v[178:181], v[64:67]
	v_mfma_f32_16x16x32_bf16 v[60:63], v[140:143], v[174:177], v[60:63]
	v_mfma_f32_16x16x32_bf16 v[60:63], v[144:147], v[178:181], v[60:63]
	v_mfma_f32_16x16x32_bf16 v[48:51], v[132:135], v[188:191], v[48:51]
	v_mfma_f32_16x16x32_bf16 v[48:51], v[136:139], v[192:195], v[48:51]
	v_mfma_f32_16x16x32_bf16 v[44:47], v[140:143], v[188:191], v[44:47]
	v_mfma_f32_16x16x32_bf16 v[44:47], v[144:147], v[192:195], v[44:47]
	v_mfma_f32_16x16x32_bf16 v[30:33], v[132:135], v[206:209], v[30:33]
	v_mfma_f32_16x16x32_bf16 v[30:33], v[136:139], v[210:213], v[30:33]
	v_mfma_f32_16x16x32_bf16 v[26:29], v[140:143], v[206:209], v[26:29]
	v_mfma_f32_16x16x32_bf16 v[26:29], v[144:147], v[210:213], v[26:29]
	v_mfma_f32_16x16x32_bf16 v[14:17], v[132:135], v[214:217], v[14:17]
	v_mfma_f32_16x16x32_bf16 v[14:17], v[136:139], v[218:221], v[14:17]
	v_mfma_f32_16x16x32_bf16 v[10:13], v[140:143], v[214:217], v[10:13]
	v_mfma_f32_16x16x32_bf16 v[10:13], v[144:147], v[218:221], v[10:13]
	v_mfma_f32_16x16x32_bf16 v[56:59], v[148:151], v[174:177], v[56:59]
	v_mfma_f32_16x16x32_bf16 v[56:59], v[152:155], v[178:181], v[56:59]
	v_mfma_f32_16x16x32_bf16 v[52:55], v[156:159], v[174:177], v[52:55]
	v_mfma_f32_16x16x32_bf16 v[52:55], v[170:173], v[178:181], v[52:55]
	v_mfma_f32_16x16x32_bf16 v[40:43], v[148:151], v[188:191], v[40:43]
	v_mfma_f32_16x16x32_bf16 v[40:43], v[152:155], v[192:195], v[40:43]
	v_mfma_f32_16x16x32_bf16 v[36:39], v[156:159], v[188:191], v[36:39]
	v_mfma_f32_16x16x32_bf16 v[36:39], v[170:173], v[192:195], v[36:39]
	v_mfma_f32_16x16x32_bf16 v[22:25], v[148:151], v[206:209], v[22:25]
	v_mfma_f32_16x16x32_bf16 v[22:25], v[152:155], v[210:213], v[22:25]
	v_mfma_f32_16x16x32_bf16 v[18:21], v[156:159], v[206:209], v[18:21]
	v_mfma_f32_16x16x32_bf16 v[18:21], v[170:173], v[210:213], v[18:21]
	v_mfma_f32_16x16x32_bf16 v[6:9], v[148:151], v[214:217], v[6:9]
	v_mfma_f32_16x16x32_bf16 v[6:9], v[152:155], v[218:221], v[6:9]
	v_mfma_f32_16x16x32_bf16 v[2:5], v[156:159], v[214:217], v[2:5]
	v_mfma_f32_16x16x32_bf16 v[2:5], v[170:173], v[218:221], v[2:5]
	s_barrier
	s_setprio 0
	s_add_i32 s43, 0, 0x18000
	s_add_i32 s60, 0, 0x1c000
	v_add_u32_e32 v144, s43, v186
	v_add_u32_e32 v170, s60, v186
	ds_read_b128 v[132:135], v144
	ds_read_b128 v[136:139], v144 offset:1024
	ds_read_b128 v[140:143], v144 offset:2048
	ds_read_b128 v[144:147], v144 offset:3072
	ds_read_b128 v[148:151], v170
	ds_read_b128 v[152:155], v170 offset:1024
	ds_read_b128 v[156:159], v170 offset:2048
	ds_read_b128 v[170:173], v170 offset:3072
	s_add_u32 s24, s30, 0x160000
	s_addc_u32 s25, s31, 0
	s_mov_b32 m0, s45
	v_lshl_add_u64 v[222:223], s[24:25], 0, v[160:161]
	ds_read_b128 v[174:177], v187 offset:32768
	ds_read_b128 v[178:181], v187 offset:33792
	ds_read_b128 v[188:191], v187 offset:34816
	ds_read_b128 v[192:195], v187 offset:35840
	ds_read_b128 v[206:209], v187 offset:36864
	ds_read_b128 v[210:213], v187 offset:37888
	ds_read_b128 v[214:217], v187 offset:38912
	ds_read_b128 v[218:221], v187 offset:39936
	global_load_lds_dwordx4 v[222:223], off
	v_lshl_add_u64 v[222:223], s[24:25], 0, v[162:163]
	s_mov_b32 m0, s46
	s_nop 0
	global_load_lds_dwordx4 v[222:223], off
	s_waitcnt vmcnt(8)
	s_waitcnt lgkmcnt(0)
	s_setprio 1
	s_barrier
	v_mfma_f32_16x16x32_bf16 v[128:131], v[132:135], v[174:177], v[128:131]
	v_mfma_f32_16x16x32_bf16 v[128:131], v[136:139], v[178:181], v[128:131]
	v_mfma_f32_16x16x32_bf16 v[124:127], v[140:143], v[174:177], v[124:127]
	v_mfma_f32_16x16x32_bf16 v[124:127], v[144:147], v[178:181], v[124:127]
	v_mfma_f32_16x16x32_bf16 v[112:115], v[132:135], v[188:191], v[112:115]
	v_mfma_f32_16x16x32_bf16 v[112:115], v[136:139], v[192:195], v[112:115]
	v_mfma_f32_16x16x32_bf16 v[108:111], v[140:143], v[188:191], v[108:111]
	v_mfma_f32_16x16x32_bf16 v[108:111], v[144:147], v[192:195], v[108:111]
	v_mfma_f32_16x16x32_bf16 v[96:99], v[132:135], v[206:209], v[96:99]
	v_mfma_f32_16x16x32_bf16 v[96:99], v[136:139], v[210:213], v[96:99]
	v_mfma_f32_16x16x32_bf16 v[92:95], v[140:143], v[206:209], v[92:95]
	v_mfma_f32_16x16x32_bf16 v[92:95], v[144:147], v[210:213], v[92:95]
	v_mfma_f32_16x16x32_bf16 v[80:83], v[132:135], v[214:217], v[80:83]
	v_mfma_f32_16x16x32_bf16 v[80:83], v[136:139], v[218:221], v[80:83]
	v_mfma_f32_16x16x32_bf16 v[76:79], v[140:143], v[214:217], v[76:79]
	v_mfma_f32_16x16x32_bf16 v[76:79], v[144:147], v[218:221], v[76:79]
	v_mfma_f32_16x16x32_bf16 v[120:123], v[148:151], v[174:177], v[120:123]
	v_mfma_f32_16x16x32_bf16 v[120:123], v[152:155], v[178:181], v[120:123]
	v_mfma_f32_16x16x32_bf16 v[116:119], v[156:159], v[174:177], v[116:119]
	v_mfma_f32_16x16x32_bf16 v[116:119], v[170:173], v[178:181], v[116:119]
	v_mfma_f32_16x16x32_bf16 v[104:107], v[148:151], v[188:191], v[104:107]
	v_mfma_f32_16x16x32_bf16 v[104:107], v[152:155], v[192:195], v[104:107]
	v_mfma_f32_16x16x32_bf16 v[100:103], v[156:159], v[188:191], v[100:103]
	v_mfma_f32_16x16x32_bf16 v[100:103], v[170:173], v[192:195], v[100:103]
	v_mfma_f32_16x16x32_bf16 v[88:91], v[148:151], v[206:209], v[88:91]
	v_mfma_f32_16x16x32_bf16 v[88:91], v[152:155], v[210:213], v[88:91]
	v_mfma_f32_16x16x32_bf16 v[84:87], v[156:159], v[206:209], v[84:87]
	v_mfma_f32_16x16x32_bf16 v[84:87], v[170:173], v[210:213], v[84:87]
	v_mfma_f32_16x16x32_bf16 v[72:75], v[148:151], v[214:217], v[72:75]
	v_mfma_f32_16x16x32_bf16 v[72:75], v[152:155], v[218:221], v[72:75]
	v_mfma_f32_16x16x32_bf16 v[68:71], v[156:159], v[214:217], v[68:71]
	v_mfma_f32_16x16x32_bf16 v[68:71], v[170:173], v[218:221], v[68:71]
	s_barrier
	s_setprio 0
	s_add_i32 s24, s43, s38
	v_lshl_add_u64 v[182:183], v[182:183], 0, s[18:19]
	s_mov_b32 m0, s24
	ds_read_b128 v[174:177], v187 offset:49152
	ds_read_b128 v[178:181], v187 offset:50176
	ds_read_b128 v[188:191], v187 offset:51200
	ds_read_b128 v[192:195], v187 offset:52224
	ds_read_b128 v[206:209], v187 offset:53248
	ds_read_b128 v[210:213], v187 offset:54272
	ds_read_b128 v[214:217], v187 offset:55296
	ds_read_b128 v[218:221], v187 offset:56320
	global_load_lds_dwordx4 v[182:183], off
	s_add_i32 m0, s24, 0x2000
	s_add_u32 s24, s28, 0x160080
	v_lshl_add_u64 v[182:183], v[196:197], 0, s[18:19]
	s_addc_u32 s25, s29, 0
	s_add_i32 s28, s60, s38
	global_load_lds_dwordx4 v[182:183], off
	v_lshl_add_u64 v[182:183], s[24:25], 0, v[34:35]
	s_mov_b32 m0, s28
	s_nop 0
	global_load_lds_dwordx4 v[182:183], off
	v_lshl_add_u64 v[182:183], s[24:25], 0, v[164:165]
	s_add_i32 m0, s28, 0x2000
	s_nop 0
	global_load_lds_dwordx4 v[182:183], off
	v_lshl_add_u64 v[182:183], v[198:199], 0, s[18:19]
	s_mov_b32 m0, s47
	s_nop 0
	global_load_lds_dwordx4 v[182:183], off
	v_lshl_add_u64 v[182:183], v[200:201], 0, s[18:19]
	s_mov_b32 m0, s52
	s_nop 0
	global_load_lds_dwordx4 v[182:183], off
	s_waitcnt vmcnt(8)
	s_waitcnt lgkmcnt(0)
	s_setprio 1
	s_barrier
	v_mfma_f32_16x16x32_bf16 v[64:67], v[132:135], v[174:177], v[64:67]
	v_mfma_f32_16x16x32_bf16 v[64:67], v[136:139], v[178:181], v[64:67]
	v_mfma_f32_16x16x32_bf16 v[60:63], v[140:143], v[174:177], v[60:63]
	v_mfma_f32_16x16x32_bf16 v[60:63], v[144:147], v[178:181], v[60:63]
	v_mfma_f32_16x16x32_bf16 v[48:51], v[132:135], v[188:191], v[48:51]
	v_mfma_f32_16x16x32_bf16 v[48:51], v[136:139], v[192:195], v[48:51]
	v_mfma_f32_16x16x32_bf16 v[44:47], v[140:143], v[188:191], v[44:47]
	v_mfma_f32_16x16x32_bf16 v[44:47], v[144:147], v[192:195], v[44:47]
	v_mfma_f32_16x16x32_bf16 v[30:33], v[132:135], v[206:209], v[30:33]
	v_mfma_f32_16x16x32_bf16 v[30:33], v[136:139], v[210:213], v[30:33]
	v_mfma_f32_16x16x32_bf16 v[26:29], v[140:143], v[206:209], v[26:29]
	v_mfma_f32_16x16x32_bf16 v[26:29], v[144:147], v[210:213], v[26:29]
	v_mfma_f32_16x16x32_bf16 v[14:17], v[132:135], v[214:217], v[14:17]
	v_mfma_f32_16x16x32_bf16 v[14:17], v[136:139], v[218:221], v[14:17]
	v_mfma_f32_16x16x32_bf16 v[10:13], v[140:143], v[214:217], v[10:13]
	v_mfma_f32_16x16x32_bf16 v[10:13], v[144:147], v[218:221], v[10:13]
	v_mfma_f32_16x16x32_bf16 v[56:59], v[148:151], v[174:177], v[56:59]
	v_mfma_f32_16x16x32_bf16 v[56:59], v[152:155], v[178:181], v[56:59]
	v_mfma_f32_16x16x32_bf16 v[52:55], v[156:159], v[174:177], v[52:55]
	v_mfma_f32_16x16x32_bf16 v[52:55], v[170:173], v[178:181], v[52:55]
	v_mfma_f32_16x16x32_bf16 v[40:43], v[148:151], v[188:191], v[40:43]
	v_mfma_f32_16x16x32_bf16 v[40:43], v[152:155], v[192:195], v[40:43]
	v_mfma_f32_16x16x32_bf16 v[36:39], v[156:159], v[188:191], v[36:39]
	v_mfma_f32_16x16x32_bf16 v[36:39], v[170:173], v[192:195], v[36:39]
	v_mfma_f32_16x16x32_bf16 v[22:25], v[148:151], v[206:209], v[22:25]
	v_mfma_f32_16x16x32_bf16 v[22:25], v[152:155], v[210:213], v[22:25]
	v_mfma_f32_16x16x32_bf16 v[18:21], v[156:159], v[206:209], v[18:21]
	v_mfma_f32_16x16x32_bf16 v[18:21], v[170:173], v[210:213], v[18:21]
	v_mfma_f32_16x16x32_bf16 v[6:9], v[148:151], v[214:217], v[6:9]
	v_mfma_f32_16x16x32_bf16 v[6:9], v[152:155], v[218:221], v[6:9]
	v_mfma_f32_16x16x32_bf16 v[2:5], v[156:159], v[214:217], v[2:5]
	v_mfma_f32_16x16x32_bf16 v[2:5], v[170:173], v[218:221], v[2:5]
	s_barrier
	s_setprio 0
	s_add_i32 s42, s42, 2
	s_add_u32 s11, s11, 0x100
	s_addc_u32 s13, s13, 0
	s_cmpk_gt_u32 s42, 0x55
	s_mov_b64 s[24:25], s[26:27]
	s_cbranch_scc0 .LBB0_546
	s_and_b64 vcc, exec, s[16:17]
	s_cbranch_vccz .LBB0_549
	s_barrier

.LBB0_807:
	v_mfma_f32_16x16x32_bf16 v[128:131], v[148:151], v[188:191], v[128:131]
	v_mfma_f32_16x16x32_bf16 v[128:131], v[152:155], v[192:195], v[128:131]
	v_mfma_f32_16x16x32_bf16 v[124:127], v[156:159], v[188:191], v[124:127]
	v_mfma_f32_16x16x32_bf16 v[124:127], v[160:163], v[192:195], v[124:127]
	v_mfma_f32_16x16x32_bf16 v[112:115], v[148:151], v[180:183], v[112:115]
	v_mfma_f32_16x16x32_bf16 v[112:115], v[152:155], v[184:187], v[112:115]
	v_mfma_f32_16x16x32_bf16 v[108:111], v[156:159], v[180:183], v[108:111]
	v_mfma_f32_16x16x32_bf16 v[108:111], v[160:163], v[184:187], v[108:111]
	v_mfma_f32_16x16x32_bf16 v[96:99], v[148:151], v[172:175], v[96:99]
	v_mfma_f32_16x16x32_bf16 v[96:99], v[152:155], v[176:179], v[96:99]
	v_mfma_f32_16x16x32_bf16 v[92:95], v[156:159], v[172:175], v[92:95]
	v_mfma_f32_16x16x32_bf16 v[92:95], v[160:163], v[176:179], v[92:95]
	v_mfma_f32_16x16x32_bf16 v[80:83], v[148:151], v[164:167], v[80:83]
	v_mfma_f32_16x16x32_bf16 v[80:83], v[152:155], v[168:171], v[80:83]
	v_mfma_f32_16x16x32_bf16 v[76:79], v[156:159], v[164:167], v[76:79]
	v_mfma_f32_16x16x32_bf16 v[76:79], v[160:163], v[168:171], v[76:79]
	v_mfma_f32_16x16x32_bf16 v[120:123], v[132:135], v[188:191], v[120:123]
	v_mfma_f32_16x16x32_bf16 v[120:123], v[136:139], v[192:195], v[120:123]
	v_mfma_f32_16x16x32_bf16 v[116:119], v[140:143], v[188:191], v[116:119]
	v_mfma_f32_16x16x32_bf16 v[116:119], v[144:147], v[192:195], v[116:119]
	v_mfma_f32_16x16x32_bf16 v[104:107], v[132:135], v[180:183], v[104:107]
	v_mfma_f32_16x16x32_bf16 v[104:107], v[136:139], v[184:187], v[104:107]
	v_mfma_f32_16x16x32_bf16 v[100:103], v[140:143], v[180:183], v[100:103]
	v_mfma_f32_16x16x32_bf16 v[100:103], v[144:147], v[184:187], v[100:103]
	v_mfma_f32_16x16x32_bf16 v[88:91], v[132:135], v[172:175], v[88:91]
	v_mfma_f32_16x16x32_bf16 v[88:91], v[136:139], v[176:179], v[88:91]
	v_mfma_f32_16x16x32_bf16 v[84:87], v[140:143], v[172:175], v[84:87]
	v_mfma_f32_16x16x32_bf16 v[84:87], v[144:147], v[176:179], v[84:87]
	v_mfma_f32_16x16x32_bf16 v[72:75], v[132:135], v[164:167], v[72:75]
	v_mfma_f32_16x16x32_bf16 v[72:75], v[136:139], v[168:171], v[72:75]
	v_mfma_f32_16x16x32_bf16 v[68:71], v[140:143], v[164:167], v[68:71]
	v_mfma_f32_16x16x32_bf16 v[68:71], v[144:147], v[168:171], v[68:71]
	s_barrier
	s_setprio 0
	s_mov_b32 m0, s52
	v_lshl_add_u64 v[198:199], s[36:37], 0, v[208:209]
	s_add_u32 s70, s36, 0x80000
	ds_read_b128 v[164:167], v240 offset:16384
	ds_read_b128 v[168:171], v240 offset:17408
	ds_read_b128 v[172:175], v240 offset:18432
	ds_read_b128 v[176:179], v240 offset:19456
	ds_read_b128 v[180:183], v240 offset:20480
	ds_read_b128 v[184:187], v240 offset:21504
	ds_read_b128 v[188:191], v240 offset:22528
	ds_read_b128 v[192:195], v240 offset:23552
	global_load_lds_dwordx4 v[198:199], off
	v_lshl_add_u64 v[200:201], s[36:37], 0, v[212:213]
	s_mov_b32 m0, s54
	s_addc_u32 s71, s37, 0
	global_load_lds_dwordx4 v[200:201], off
	v_lshl_add_u64 v[242:243], s[70:71], 0, v[208:209]
	s_mov_b32 m0, s55
	v_lshl_add_u64 v[244:245], s[42:43], 0, v[210:211]
	global_load_lds_dwordx4 v[242:243], off
	v_lshl_add_u64 v[242:243], s[70:71], 0, v[212:213]
	s_mov_b32 m0, s59
	s_nop 0
	global_load_lds_dwordx4 v[242:243], off
	v_lshl_add_u64 v[242:243], s[42:43], 0, v[206:207]
	s_mov_b32 m0, s47
	s_nop 0
	global_load_lds_dwordx4 v[242:243], off
	s_mov_b32 m0, s60
	s_nop 0
	global_load_lds_dwordx4 v[244:245], off
	s_waitcnt vmcnt(8)
	s_waitcnt lgkmcnt(0)
	s_setprio 1
	s_barrier
	v_mfma_f32_16x16x32_bf16 v[64:67], v[148:151], v[164:167], v[64:67]
	v_mfma_f32_16x16x32_bf16 v[64:67], v[152:155], v[168:171], v[64:67]
	v_mfma_f32_16x16x32_bf16 v[60:63], v[156:159], v[164:167], v[60:63]
	v_mfma_f32_16x16x32_bf16 v[60:63], v[160:163], v[168:171], v[60:63]
	v_mfma_f32_16x16x32_bf16 v[48:51], v[148:151], v[172:175], v[48:51]
	v_mfma_f32_16x16x32_bf16 v[48:51], v[152:155], v[176:179], v[48:51]
	v_mfma_f32_16x16x32_bf16 v[44:47], v[156:159], v[172:175], v[44:47]
	v_mfma_f32_16x16x32_bf16 v[44:47], v[160:163], v[176:179], v[44:47]
	v_mfma_f32_16x16x32_bf16 v[30:33], v[148:151], v[180:183], v[30:33]
	v_mfma_f32_16x16x32_bf16 v[30:33], v[152:155], v[184:187], v[30:33]
	v_mfma_f32_16x16x32_bf16 v[26:29], v[156:159], v[180:183], v[26:29]
	v_mfma_f32_16x16x32_bf16 v[26:29], v[160:163], v[184:187], v[26:29]
	v_mfma_f32_16x16x32_bf16 v[14:17], v[148:151], v[188:191], v[14:17]
	v_mfma_f32_16x16x32_bf16 v[14:17], v[152:155], v[192:195], v[14:17]
	v_mfma_f32_16x16x32_bf16 v[10:13], v[156:159], v[188:191], v[10:13]
	v_mfma_f32_16x16x32_bf16 v[10:13], v[160:163], v[192:195], v[10:13]
	v_mfma_f32_16x16x32_bf16 v[56:59], v[132:135], v[164:167], v[56:59]
	v_mfma_f32_16x16x32_bf16 v[56:59], v[136:139], v[168:171], v[56:59]
	v_mfma_f32_16x16x32_bf16 v[52:55], v[140:143], v[164:167], v[52:55]
	v_mfma_f32_16x16x32_bf16 v[52:55], v[144:147], v[168:171], v[52:55]
	v_mfma_f32_16x16x32_bf16 v[40:43], v[132:135], v[172:175], v[40:43]
	v_mfma_f32_16x16x32_bf16 v[40:43], v[136:139], v[176:179], v[40:43]
	v_mfma_f32_16x16x32_bf16 v[36:39], v[140:143], v[172:175], v[36:39]
	v_mfma_f32_16x16x32_bf16 v[36:39], v[144:147], v[176:179], v[36:39]
	v_mfma_f32_16x16x32_bf16 v[22:25], v[132:135], v[180:183], v[22:25]
	v_mfma_f32_16x16x32_bf16 v[22:25], v[136:139], v[184:187], v[22:25]
	v_mfma_f32_16x16x32_bf16 v[18:21], v[140:143], v[180:183], v[18:21]
	v_mfma_f32_16x16x32_bf16 v[18:21], v[144:147], v[184:187], v[18:21]
	v_mfma_f32_16x16x32_bf16 v[6:9], v[132:135], v[188:191], v[6:9]
	v_mfma_f32_16x16x32_bf16 v[6:9], v[136:139], v[192:195], v[6:9]
	v_mfma_f32_16x16x32_bf16 v[2:5], v[140:143], v[188:191], v[2:5]
	v_mfma_f32_16x16x32_bf16 v[2:5], v[144:147], v[192:195], v[2:5]
	s_barrier
	s_setprio 0
	s_add_i32 s69, 0, 0x18000
	v_add_u32_e32 v34, s69, v227
	s_add_i32 s70, 0, 0x1c000
	ds_read_b128 v[132:135], v34
	ds_read_b128 v[136:139], v34 offset:1024
	ds_read_b128 v[140:143], v34 offset:2048
	ds_read_b128 v[144:147], v34 offset:3072
	v_add_u32_e32 v34, s70, v227
	ds_read_b128 v[148:151], v34
	ds_read_b128 v[152:155], v34 offset:1024
	ds_read_b128 v[156:159], v34 offset:2048
	ds_read_b128 v[160:163], v34 offset:3072
	s_add_u32 s42, s42, 0x80000
	s_addc_u32 s43, s43, 0
	s_mov_b32 m0, s61
	v_lshl_add_u64 v[246:247], s[42:43], 0, v[206:207]
	ds_read_b128 v[164:167], v240 offset:32768
	ds_read_b128 v[168:171], v240 offset:33792
	ds_read_b128 v[172:175], v240 offset:34816
	ds_read_b128 v[176:179], v240 offset:35840
	ds_read_b128 v[180:183], v240 offset:36864
	ds_read_b128 v[184:187], v240 offset:37888
	ds_read_b128 v[188:191], v240 offset:38912
	ds_read_b128 v[192:195], v240 offset:39936
	global_load_lds_dwordx4 v[246:247], off
	v_lshl_add_u64 v[246:247], s[42:43], 0, v[210:211]
	s_mov_b32 m0, s62
	s_nop 0
	global_load_lds_dwordx4 v[246:247], off
	s_waitcnt vmcnt(8)
	s_waitcnt lgkmcnt(0)
	s_setprio 1
	s_barrier
	v_mfma_f32_16x16x32_bf16 v[128:131], v[132:135], v[164:167], v[128:131]
	v_mfma_f32_16x16x32_bf16 v[128:131], v[136:139], v[168:171], v[128:131]
	v_mfma_f32_16x16x32_bf16 v[124:127], v[140:143], v[164:167], v[124:127]
	v_mfma_f32_16x16x32_bf16 v[124:127], v[144:147], v[168:171], v[124:127]
	v_mfma_f32_16x16x32_bf16 v[112:115], v[132:135], v[172:175], v[112:115]
	v_mfma_f32_16x16x32_bf16 v[112:115], v[136:139], v[176:179], v[112:115]
	v_mfma_f32_16x16x32_bf16 v[108:111], v[140:143], v[172:175], v[108:111]
	v_mfma_f32_16x16x32_bf16 v[108:111], v[144:147], v[176:179], v[108:111]
	v_mfma_f32_16x16x32_bf16 v[96:99], v[132:135], v[180:183], v[96:99]
	v_mfma_f32_16x16x32_bf16 v[96:99], v[136:139], v[184:187], v[96:99]
	v_mfma_f32_16x16x32_bf16 v[92:95], v[140:143], v[180:183], v[92:95]
	v_mfma_f32_16x16x32_bf16 v[92:95], v[144:147], v[184:187], v[92:95]
	v_mfma_f32_16x16x32_bf16 v[80:83], v[132:135], v[188:191], v[80:83]
	v_mfma_f32_16x16x32_bf16 v[80:83], v[136:139], v[192:195], v[80:83]
	v_mfma_f32_16x16x32_bf16 v[76:79], v[140:143], v[188:191], v[76:79]
	v_mfma_f32_16x16x32_bf16 v[76:79], v[144:147], v[192:195], v[76:79]
	v_mfma_f32_16x16x32_bf16 v[120:123], v[148:151], v[164:167], v[120:123]
	v_mfma_f32_16x16x32_bf16 v[120:123], v[152:155], v[168:171], v[120:123]
	v_mfma_f32_16x16x32_bf16 v[116:119], v[156:159], v[164:167], v[116:119]
	v_mfma_f32_16x16x32_bf16 v[116:119], v[160:163], v[168:171], v[116:119]
	v_mfma_f32_16x16x32_bf16 v[104:107], v[148:151], v[172:175], v[104:107]
	v_mfma_f32_16x16x32_bf16 v[104:107], v[152:155], v[176:179], v[104:107]
	v_mfma_f32_16x16x32_bf16 v[100:103], v[156:159], v[172:175], v[100:103]
	v_mfma_f32_16x16x32_bf16 v[100:103], v[160:163], v[176:179], v[100:103]
	v_mfma_f32_16x16x32_bf16 v[88:91], v[148:151], v[180:183], v[88:91]
	v_mfma_f32_16x16x32_bf16 v[88:91], v[152:155], v[184:187], v[88:91]
	v_mfma_f32_16x16x32_bf16 v[84:87], v[156:159], v[180:183], v[84:87]
	v_mfma_f32_16x16x32_bf16 v[84:87], v[160:163], v[184:187], v[84:87]
	v_mfma_f32_16x16x32_bf16 v[72:75], v[148:151], v[188:191], v[72:75]
	v_mfma_f32_16x16x32_bf16 v[72:75], v[152:155], v[192:195], v[72:75]
	v_mfma_f32_16x16x32_bf16 v[68:71], v[156:159], v[188:191], v[68:71]
	v_mfma_f32_16x16x32_bf16 v[68:71], v[160:163], v[192:195], v[68:71]
	s_barrier
	s_setprio 0
	s_add_i32 s42, s69, s46
	v_lshl_add_u64 v[198:199], v[198:199], 0, s[18:19]
	s_mov_b32 m0, s42
	ds_read_b128 v[164:167], v240 offset:49152
	ds_read_b128 v[168:171], v240 offset:50176
	ds_read_b128 v[172:175], v240 offset:51200
	ds_read_b128 v[176:179], v240 offset:52224
	ds_read_b128 v[180:183], v240 offset:53248
	ds_read_b128 v[184:187], v240 offset:54272
	ds_read_b128 v[188:191], v240 offset:55296
	ds_read_b128 v[192:195], v240 offset:56320
	global_load_lds_dwordx4 v[198:199], off
	s_add_i32 m0, s42, 0x2000
	s_add_u32 s36, s36, 0x80080
	v_lshl_add_u64 v[198:199], v[200:201], 0, s[18:19]
	s_addc_u32 s37, s37, 0
	s_add_i32 s42, s70, s46
	global_load_lds_dwordx4 v[198:199], off
	v_lshl_add_u64 v[198:199], s[36:37], 0, v[208:209]
	s_mov_b32 m0, s42
	s_nop 0
	global_load_lds_dwordx4 v[198:199], off
	v_lshl_add_u64 v[198:199], s[36:37], 0, v[212:213]
	s_add_i32 m0, s42, 0x2000
	s_nop 0
	global_load_lds_dwordx4 v[198:199], off
	v_lshl_add_u64 v[198:199], v[242:243], 0, s[18:19]
	s_mov_b32 m0, s63
	s_nop 0
	global_load_lds_dwordx4 v[198:199], off
	v_lshl_add_u64 v[198:199], v[244:245], 0, s[18:19]
	s_mov_b32 m0, s64
	s_nop 0
	global_load_lds_dwordx4 v[198:199], off
	s_waitcnt vmcnt(8)
	s_waitcnt lgkmcnt(0)
	s_setprio 1
	s_barrier
	v_mfma_f32_16x16x32_bf16 v[64:67], v[132:135], v[164:167], v[64:67]
	v_mfma_f32_16x16x32_bf16 v[64:67], v[136:139], v[168:171], v[64:67]
	v_mfma_f32_16x16x32_bf16 v[60:63], v[140:143], v[164:167], v[60:63]
	v_mfma_f32_16x16x32_bf16 v[60:63], v[144:147], v[168:171], v[60:63]
	v_mfma_f32_16x16x32_bf16 v[48:51], v[132:135], v[172:175], v[48:51]
	v_mfma_f32_16x16x32_bf16 v[48:51], v[136:139], v[176:179], v[48:51]
	v_mfma_f32_16x16x32_bf16 v[44:47], v[140:143], v[172:175], v[44:47]
	v_mfma_f32_16x16x32_bf16 v[44:47], v[144:147], v[176:179], v[44:47]
	v_mfma_f32_16x16x32_bf16 v[30:33], v[132:135], v[180:183], v[30:33]
	v_mfma_f32_16x16x32_bf16 v[30:33], v[136:139], v[184:187], v[30:33]
	v_mfma_f32_16x16x32_bf16 v[26:29], v[140:143], v[180:183], v[26:29]
	v_mfma_f32_16x16x32_bf16 v[26:29], v[144:147], v[184:187], v[26:29]
	v_mfma_f32_16x16x32_bf16 v[14:17], v[132:135], v[188:191], v[14:17]
	v_mfma_f32_16x16x32_bf16 v[14:17], v[136:139], v[192:195], v[14:17]
	v_mfma_f32_16x16x32_bf16 v[10:13], v[140:143], v[188:191], v[10:13]
	v_mfma_f32_16x16x32_bf16 v[10:13], v[144:147], v[192:195], v[10:13]
	v_mfma_f32_16x16x32_bf16 v[56:59], v[148:151], v[164:167], v[56:59]
	v_mfma_f32_16x16x32_bf16 v[56:59], v[152:155], v[168:171], v[56:59]
	v_mfma_f32_16x16x32_bf16 v[52:55], v[156:159], v[164:167], v[52:55]
	v_mfma_f32_16x16x32_bf16 v[52:55], v[160:163], v[168:171], v[52:55]
	v_mfma_f32_16x16x32_bf16 v[40:43], v[148:151], v[172:175], v[40:43]
	v_mfma_f32_16x16x32_bf16 v[40:43], v[152:155], v[176:179], v[40:43]
	v_mfma_f32_16x16x32_bf16 v[36:39], v[156:159], v[172:175], v[36:39]
	v_mfma_f32_16x16x32_bf16 v[36:39], v[160:163], v[176:179], v[36:39]
	v_mfma_f32_16x16x32_bf16 v[22:25], v[148:151], v[180:183], v[22:25]
	v_mfma_f32_16x16x32_bf16 v[22:25], v[152:155], v[184:187], v[22:25]
	v_mfma_f32_16x16x32_bf16 v[18:21], v[156:159], v[180:183], v[18:21]
	v_mfma_f32_16x16x32_bf16 v[18:21], v[160:163], v[184:187], v[18:21]
	v_mfma_f32_16x16x32_bf16 v[6:9], v[148:151], v[188:191], v[6:9]
	v_mfma_f32_16x16x32_bf16 v[6:9], v[152:155], v[192:195], v[6:9]
	v_mfma_f32_16x16x32_bf16 v[2:5], v[156:159], v[188:191], v[2:5]
	v_mfma_f32_16x16x32_bf16 v[2:5], v[160:163], v[192:195], v[2:5]
	s_barrier
	s_setprio 0
	s_add_i32 s68, s68, 2
	s_add_u32 s34, s34, 0x100
	s_addc_u32 s35, s35, 0
	s_cmp_gt_u32 s68, 29
	s_cbranch_scc1 .LBB0_810
.LBB0_808:
	v_add_u32_e32 v34, 0, v227
	v_add_u32_e32 v132, 0x10000, v34
	v_add_u32_e32 v34, 0x14000, v34
	ds_read_b128 v[148:151], v132
	ds_read_b128 v[152:155], v132 offset:1024
	ds_read_b128 v[156:159], v132 offset:2048
	ds_read_b128 v[160:163], v132 offset:3072
	ds_read_b128 v[132:135], v34
	ds_read_b128 v[136:139], v34 offset:1024
	ds_read_b128 v[140:143], v34 offset:2048
	ds_read_b128 v[144:147], v34 offset:3072
	v_lshl_add_u64 v[198:199], v[222:223], 0, s[34:35]
	s_add_i32 m0, s47, 0xc000
	ds_read_b128 v[188:191], v240
	ds_read_b128 v[192:195], v240 offset:1024
	ds_read_b128 v[180:183], v240 offset:2048
	ds_read_b128 v[184:187], v240 offset:3072
	ds_read_b128 v[172:175], v240 offset:4096
	ds_read_b128 v[176:179], v240 offset:5120
	ds_read_b128 v[164:167], v240 offset:6144
	ds_read_b128 v[168:171], v240 offset:7168
	global_load_lds_dwordx4 v[198:199], off
	v_lshl_add_u64 v[198:199], v[224:225], 0, s[34:35]
	s_add_i32 m0, s47, 0xe000
	s_cmp_lg_u32 s34, 0
	global_load_lds_dwordx4 v[198:199], off
	s_waitcnt vmcnt(8)
	s_waitcnt lgkmcnt(0)
	s_add_u32 s36, s30, s34
	s_addc_u32 s37, s31, s35
	s_add_u32 s36, s36, 0x100
	s_addc_u32 s37, s37, 0
	s_add_u32 s69, s29, s34
	s_addc_u32 s70, s67, s35
	s_cmpk_eq_i32 s34, 0xf00
	s_cselect_b32 s43, s21, s37
	s_cselect_b32 s42, s27, s36
	s_cselect_b32 s37, s17, s70
	s_cselect_b32 s36, s66, s69
	s_cmp_lg_u32 s34, 0
	s_setprio 1
	s_barrier
	s_cbranch_scc1 .LBB0_807
	s_add_i32 m0, s47, 0x21200
	s_nop 0
	global_load_lds_dwordx4 v[220:221], off
	s_branch .LBB0_807

.LBB0_1145:
	s_add_u32 s13, s22, s28
	s_addc_u32 s36, s23, s29
	s_add_u32 s34, s13, 0x100
	s_addc_u32 s35, s36, 0
	s_and_b64 s[30:31], s[26:27], exec
	s_cselect_b32 s31, s15, s35
	s_cselect_b32 s30, s14, s34
	s_add_u32 s28, s20, s28
	s_addc_u32 s29, s21, s29
	s_add_u32 s28, s28, 0x100
	s_addc_u32 s29, s29, 0
	s_add_i32 s71, 0, 0x10000
	s_and_b64 s[26:27], s[26:27], exec
	s_cselect_b32 s35, s17, s29
	s_cselect_b32 s34, s16, s28
	s_add_u32 s44, s13, 0x18080
	s_addc_u32 s45, s36, 0
	s_add_i32 s73, s71, s46
	s_add_i32 m0, s47, 0xc000
	s_add_i32 s72, s47, 0xe000
	s_add_i32 s74, s73, 0x2000
	v_add_u32_e32 v34, s71, v82
	s_add_u32 s36, s34, 0x10000
	ds_read_b128 v[76:79], v34
	ds_read_b128 v[84:87], v34 offset:1024
	ds_read_b128 v[88:91], v34 offset:2048
	ds_read_b128 v[92:95], v34 offset:3072
	s_addc_u32 s37, s35, 0
	s_add_i32 s75, 0, 0x18000
	s_add_u32 s26, s30, 0x18000
	s_addc_u32 s27, s31, 0
	s_add_i32 s13, s75, s46
	s_add_i32 s71, s13, 0x2000
	s_add_u32 s28, s34, 0x10080
	s_addc_u32 s29, s35, 0
	v_lshl_add_u64 v[128:129], s[44:45], 0, v[68:69]
	ds_read_b128 v[96:99], v83
	ds_read_b128 v[100:103], v83 offset:1024
	ds_read_b128 v[104:107], v83 offset:2048
	ds_read_b128 v[108:111], v83 offset:3072
	ds_read_b128 v[112:115], v83 offset:4096
	ds_read_b128 v[116:119], v83 offset:5120
	ds_read_b128 v[120:123], v83 offset:6144
	ds_read_b128 v[124:127], v83 offset:7168
	global_load_lds_dwordx4 v[128:129], off
	v_lshl_add_u64 v[128:129], s[44:45], 0, v[72:73]
	s_mov_b32 m0, s72
	s_nop 0
	global_load_lds_dwordx4 v[128:129], off
	s_waitcnt vmcnt(8)
	s_waitcnt lgkmcnt(0)
	s_setprio 1
	s_barrier
	v_mfma_f32_16x16x32_bf16 v[64:67], v[76:79], v[96:99], v[64:67]
	v_mfma_f32_16x16x32_bf16 v[64:67], v[84:87], v[100:103], v[64:67]
	v_mfma_f32_16x16x32_bf16 v[60:63], v[88:91], v[96:99], v[60:63]
	v_mfma_f32_16x16x32_bf16 v[60:63], v[92:95], v[100:103], v[60:63]
	v_mfma_f32_16x16x32_bf16 v[56:59], v[76:79], v[104:107], v[56:59]
	v_mfma_f32_16x16x32_bf16 v[56:59], v[84:87], v[108:111], v[56:59]
	v_mfma_f32_16x16x32_bf16 v[52:55], v[88:91], v[104:107], v[52:55]
	v_mfma_f32_16x16x32_bf16 v[52:55], v[92:95], v[108:111], v[52:55]
	v_mfma_f32_16x16x32_bf16 v[48:51], v[76:79], v[112:115], v[48:51]
	v_mfma_f32_16x16x32_bf16 v[48:51], v[84:87], v[116:119], v[48:51]
	v_mfma_f32_16x16x32_bf16 v[44:47], v[88:91], v[112:115], v[44:47]
	v_mfma_f32_16x16x32_bf16 v[44:47], v[92:95], v[116:119], v[44:47]
	v_mfma_f32_16x16x32_bf16 v[40:43], v[76:79], v[120:123], v[40:43]
	v_mfma_f32_16x16x32_bf16 v[40:43], v[84:87], v[124:127], v[40:43]
	v_mfma_f32_16x16x32_bf16 v[36:39], v[88:91], v[120:123], v[36:39]
	v_mfma_f32_16x16x32_bf16 v[36:39], v[92:95], v[124:127], v[36:39]
	s_barrier
	s_setprio 0
	s_mov_b32 m0, s73
	v_lshl_add_u64 v[128:129], s[34:35], 0, v[70:71]
	ds_read_b128 v[96:99], v83 offset:16384
	ds_read_b128 v[100:103], v83 offset:17408
	ds_read_b128 v[104:107], v83 offset:18432
	ds_read_b128 v[108:111], v83 offset:19456
	ds_read_b128 v[112:115], v83 offset:20480
	ds_read_b128 v[116:119], v83 offset:21504
	ds_read_b128 v[120:123], v83 offset:22528
	ds_read_b128 v[124:127], v83 offset:23552
	global_load_lds_dwordx4 v[128:129], off
	v_lshl_add_u64 v[130:131], s[34:35], 0, v[74:75]
	s_mov_b32 m0, s74
	v_lshl_add_u64 v[132:133], s[36:37], 0, v[70:71]
	global_load_lds_dwordx4 v[130:131], off
	s_mov_b32 m0, s52
	v_lshl_add_u64 v[134:135], s[30:31], 0, v[72:73]
	global_load_lds_dwordx4 v[132:133], off
	v_lshl_add_u64 v[132:133], s[36:37], 0, v[74:75]
	s_mov_b32 m0, s54
	s_nop 0
	global_load_lds_dwordx4 v[132:133], off
	v_lshl_add_u64 v[132:133], s[30:31], 0, v[68:69]
	s_mov_b32 m0, s47
	s_nop 0
	global_load_lds_dwordx4 v[132:133], off
	s_mov_b32 m0, s55
	s_nop 0
	global_load_lds_dwordx4 v[134:135], off
	s_waitcnt vmcnt(8)
	s_waitcnt lgkmcnt(0)
	s_setprio 1
	s_barrier
	v_mfma_f32_16x16x32_bf16 v[30:33], v[76:79], v[96:99], v[30:33]
	v_mfma_f32_16x16x32_bf16 v[30:33], v[84:87], v[100:103], v[30:33]
	v_mfma_f32_16x16x32_bf16 v[26:29], v[88:91], v[96:99], v[26:29]
	v_mfma_f32_16x16x32_bf16 v[26:29], v[92:95], v[100:103], v[26:29]
	v_mfma_f32_16x16x32_bf16 v[22:25], v[76:79], v[104:107], v[22:25]
	v_mfma_f32_16x16x32_bf16 v[22:25], v[84:87], v[108:111], v[22:25]
	v_mfma_f32_16x16x32_bf16 v[18:21], v[88:91], v[104:107], v[18:21]
	v_mfma_f32_16x16x32_bf16 v[18:21], v[92:95], v[108:111], v[18:21]
	v_mfma_f32_16x16x32_bf16 v[14:17], v[76:79], v[112:115], v[14:17]
	v_mfma_f32_16x16x32_bf16 v[14:17], v[84:87], v[116:119], v[14:17]
	v_mfma_f32_16x16x32_bf16 v[10:13], v[88:91], v[112:115], v[10:13]
	v_mfma_f32_16x16x32_bf16 v[10:13], v[92:95], v[116:119], v[10:13]
	v_mfma_f32_16x16x32_bf16 v[6:9], v[76:79], v[120:123], v[6:9]
	v_mfma_f32_16x16x32_bf16 v[6:9], v[84:87], v[124:127], v[6:9]
	v_mfma_f32_16x16x32_bf16 v[2:5], v[88:91], v[120:123], v[2:5]
	v_mfma_f32_16x16x32_bf16 v[2:5], v[92:95], v[124:127], v[2:5]
	s_barrier
	s_setprio 0
	v_add_u32_e32 v34, s75, v82
	ds_read_b128 v[76:79], v34
	ds_read_b128 v[84:87], v34 offset:1024
	ds_read_b128 v[88:91], v34 offset:2048
	ds_read_b128 v[92:95], v34 offset:3072
	s_mov_b32 m0, s62
	v_lshl_add_u64 v[136:137], s[26:27], 0, v[68:69]
	ds_read_b128 v[96:99], v83 offset:32768
	ds_read_b128 v[100:103], v83 offset:33792
	ds_read_b128 v[104:107], v83 offset:34816
	ds_read_b128 v[108:111], v83 offset:35840
	ds_read_b128 v[112:115], v83 offset:36864
	ds_read_b128 v[116:119], v83 offset:37888
	ds_read_b128 v[120:123], v83 offset:38912
	ds_read_b128 v[124:127], v83 offset:39936
	global_load_lds_dwordx4 v[136:137], off
	v_lshl_add_u64 v[136:137], s[26:27], 0, v[72:73]
	s_mov_b32 m0, s63
	s_nop 0
	global_load_lds_dwordx4 v[136:137], off
	s_waitcnt vmcnt(8)
	s_waitcnt lgkmcnt(0)
	s_setprio 1
	s_barrier
	v_mfma_f32_16x16x32_bf16 v[64:67], v[76:79], v[96:99], v[64:67]
	v_mfma_f32_16x16x32_bf16 v[64:67], v[84:87], v[100:103], v[64:67]
	v_mfma_f32_16x16x32_bf16 v[60:63], v[88:91], v[96:99], v[60:63]
	v_mfma_f32_16x16x32_bf16 v[60:63], v[92:95], v[100:103], v[60:63]
	v_mfma_f32_16x16x32_bf16 v[56:59], v[76:79], v[104:107], v[56:59]
	v_mfma_f32_16x16x32_bf16 v[56:59], v[84:87], v[108:111], v[56:59]
	v_mfma_f32_16x16x32_bf16 v[52:55], v[88:91], v[104:107], v[52:55]
	v_mfma_f32_16x16x32_bf16 v[52:55], v[92:95], v[108:111], v[52:55]
	v_mfma_f32_16x16x32_bf16 v[48:51], v[76:79], v[112:115], v[48:51]
	v_mfma_f32_16x16x32_bf16 v[48:51], v[84:87], v[116:119], v[48:51]
	v_mfma_f32_16x16x32_bf16 v[44:47], v[88:91], v[112:115], v[44:47]
	v_mfma_f32_16x16x32_bf16 v[44:47], v[92:95], v[116:119], v[44:47]
	v_mfma_f32_16x16x32_bf16 v[40:43], v[76:79], v[120:123], v[40:43]
	v_mfma_f32_16x16x32_bf16 v[40:43], v[84:87], v[124:127], v[40:43]
	v_mfma_f32_16x16x32_bf16 v[36:39], v[88:91], v[120:123], v[36:39]
	v_mfma_f32_16x16x32_bf16 v[36:39], v[92:95], v[124:127], v[36:39]
	s_barrier
	s_setprio 0
	s_mov_b32 m0, s13
	v_lshl_add_u64 v[128:129], v[128:129], 0, s[18:19]
	ds_read_b128 v[96:99], v83 offset:49152
	ds_read_b128 v[100:103], v83 offset:50176
	ds_read_b128 v[104:107], v83 offset:51200
	ds_read_b128 v[108:111], v83 offset:52224
	ds_read_b128 v[112:115], v83 offset:53248
	ds_read_b128 v[116:119], v83 offset:54272
	ds_read_b128 v[120:123], v83 offset:55296
	ds_read_b128 v[124:127], v83 offset:56320
	global_load_lds_dwordx4 v[128:129], off
	v_lshl_add_u64 v[128:129], v[130:131], 0, s[18:19]
	s_mov_b32 m0, s71
	s_nop 0
	global_load_lds_dwordx4 v[128:129], off
	v_lshl_add_u64 v[128:129], s[28:29], 0, v[70:71]
	s_mov_b32 m0, s66
	s_nop 0
	global_load_lds_dwordx4 v[128:129], off
	v_lshl_add_u64 v[128:129], s[28:29], 0, v[74:75]
	s_mov_b32 m0, s67
	s_nop 0
	global_load_lds_dwordx4 v[128:129], off
	v_lshl_add_u64 v[128:129], v[132:133], 0, s[18:19]
	s_mov_b32 m0, s64
	s_nop 0
	global_load_lds_dwordx4 v[128:129], off
	v_lshl_add_u64 v[128:129], v[134:135], 0, s[18:19]
	s_mov_b32 m0, s65
	s_nop 0
	global_load_lds_dwordx4 v[128:129], off
	s_waitcnt vmcnt(8)
	s_waitcnt lgkmcnt(0)
	s_setprio 1
	s_barrier
	v_mfma_f32_16x16x32_bf16 v[30:33], v[76:79], v[96:99], v[30:33]
	v_mfma_f32_16x16x32_bf16 v[30:33], v[84:87], v[100:103], v[30:33]
	v_mfma_f32_16x16x32_bf16 v[26:29], v[88:91], v[96:99], v[26:29]
	v_mfma_f32_16x16x32_bf16 v[26:29], v[92:95], v[100:103], v[26:29]
	v_mfma_f32_16x16x32_bf16 v[22:25], v[76:79], v[104:107], v[22:25]
	v_mfma_f32_16x16x32_bf16 v[22:25], v[84:87], v[108:111], v[22:25]
	v_mfma_f32_16x16x32_bf16 v[18:21], v[88:91], v[104:107], v[18:21]
	v_mfma_f32_16x16x32_bf16 v[18:21], v[92:95], v[108:111], v[18:21]
	v_mfma_f32_16x16x32_bf16 v[14:17], v[76:79], v[112:115], v[14:17]
	v_mfma_f32_16x16x32_bf16 v[14:17], v[84:87], v[116:119], v[14:17]
	v_mfma_f32_16x16x32_bf16 v[10:13], v[88:91], v[112:115], v[10:13]
	v_mfma_f32_16x16x32_bf16 v[10:13], v[92:95], v[116:119], v[10:13]
	v_mfma_f32_16x16x32_bf16 v[6:9], v[76:79], v[120:123], v[6:9]
	v_mfma_f32_16x16x32_bf16 v[6:9], v[84:87], v[124:127], v[6:9]
	v_mfma_f32_16x16x32_bf16 v[2:5], v[88:91], v[120:123], v[2:5]
	v_mfma_f32_16x16x32_bf16 v[2:5], v[92:95], v[124:127], v[2:5]
	s_barrier
	s_setprio 0
	s_andn2_b64 vcc, exec, s[24:25]
	s_mov_b64 s[26:27], -1
	s_mov_b64 s[24:25], 0
	s_mov_b64 s[28:29], 0x100
	s_cbranch_vccz .LBB0_1145
	s_and_b64 vcc, exec, s[10:11]
	s_cbranch_vccz .LBB0_1148
	s_barrier

.LBB0_1391:
	s_add_u32 s20, s16, 0x100
	s_addc_u32 s21, s17, 0
	s_add_i32 s55, 0, 0x10000
	s_cmp_eq_u32 s54, 2
	s_cselect_b32 s25, s13, s21
	s_cselect_b32 s24, s12, s20
	v_add_u32_e32 v34, s55, v152
	s_cselect_b32 s23, s15, s45
	s_cselect_b32 s22, s14, s44
	s_add_i32 s59, 0, 0x14000
	ds_read_b128 v[144:147], v34
	ds_read_b128 v[154:157], v34 offset:1024
	ds_read_b128 v[158:161], v34 offset:2048
	ds_read_b128 v[162:165], v34 offset:3072
	v_add_u32_e32 v34, s59, v152
	ds_read_b128 v[166:169], v34
	ds_read_b128 v[170:173], v34 offset:1024
	ds_read_b128 v[174:177], v34 offset:2048
	ds_read_b128 v[178:181], v34 offset:3072
	v_lshl_add_u64 v[148:149], s[16:17], 0, v[140:141]
	s_add_i32 m0, s31, 0xc000
	ds_read_b128 v[182:185], v153
	ds_read_b128 v[186:189], v153 offset:1024
	ds_read_b128 v[190:193], v153 offset:2048
	ds_read_b128 v[194:197], v153 offset:3072
	ds_read_b128 v[206:209], v153 offset:4096
	ds_read_b128 v[210:213], v153 offset:5120
	ds_read_b128 v[214:217], v153 offset:6144
	ds_read_b128 v[218:221], v153 offset:7168
	global_load_lds_dwordx4 v[148:149], off
	v_lshl_add_u64 v[148:149], s[16:17], 0, v[142:143]
	s_add_i32 m0, s31, 0xe000
	s_nop 0
	global_load_lds_dwordx4 v[148:149], off
	s_waitcnt vmcnt(8)
	s_waitcnt lgkmcnt(0)
	s_setprio 1
	s_barrier
	v_mfma_f32_16x16x32_bf16 v[128:131], v[144:147], v[182:185], v[128:131]
	v_mfma_f32_16x16x32_bf16 v[128:131], v[154:157], v[186:189], v[128:131]
	v_mfma_f32_16x16x32_bf16 v[124:127], v[158:161], v[182:185], v[124:127]
	v_mfma_f32_16x16x32_bf16 v[124:127], v[162:165], v[186:189], v[124:127]
	v_mfma_f32_16x16x32_bf16 v[112:115], v[144:147], v[190:193], v[112:115]
	v_mfma_f32_16x16x32_bf16 v[112:115], v[154:157], v[194:197], v[112:115]
	v_mfma_f32_16x16x32_bf16 v[108:111], v[158:161], v[190:193], v[108:111]
	v_mfma_f32_16x16x32_bf16 v[108:111], v[162:165], v[194:197], v[108:111]
	v_mfma_f32_16x16x32_bf16 v[96:99], v[144:147], v[206:209], v[96:99]
	v_mfma_f32_16x16x32_bf16 v[96:99], v[154:157], v[210:213], v[96:99]
	v_mfma_f32_16x16x32_bf16 v[92:95], v[158:161], v[206:209], v[92:95]
	v_mfma_f32_16x16x32_bf16 v[92:95], v[162:165], v[210:213], v[92:95]
	v_mfma_f32_16x16x32_bf16 v[80:83], v[144:147], v[214:217], v[80:83]
	v_mfma_f32_16x16x32_bf16 v[80:83], v[154:157], v[218:221], v[80:83]
	v_mfma_f32_16x16x32_bf16 v[76:79], v[158:161], v[214:217], v[76:79]
	v_mfma_f32_16x16x32_bf16 v[76:79], v[162:165], v[218:221], v[76:79]
	v_mfma_f32_16x16x32_bf16 v[120:123], v[166:169], v[182:185], v[120:123]
	v_mfma_f32_16x16x32_bf16 v[120:123], v[170:173], v[186:189], v[120:123]
	v_mfma_f32_16x16x32_bf16 v[116:119], v[174:177], v[182:185], v[116:119]
	v_mfma_f32_16x16x32_bf16 v[116:119], v[178:181], v[186:189], v[116:119]
	v_mfma_f32_16x16x32_bf16 v[104:107], v[166:169], v[190:193], v[104:107]
	v_mfma_f32_16x16x32_bf16 v[104:107], v[170:173], v[194:197], v[104:107]
	v_mfma_f32_16x16x32_bf16 v[100:103], v[174:177], v[190:193], v[100:103]
	v_mfma_f32_16x16x32_bf16 v[100:103], v[178:181], v[194:197], v[100:103]
	v_mfma_f32_16x16x32_bf16 v[88:91], v[166:169], v[206:209], v[88:91]
	v_mfma_f32_16x16x32_bf16 v[88:91], v[170:173], v[210:213], v[88:91]
	v_mfma_f32_16x16x32_bf16 v[84:87], v[174:177], v[206:209], v[84:87]
	v_mfma_f32_16x16x32_bf16 v[84:87], v[178:181], v[210:213], v[84:87]
	v_mfma_f32_16x16x32_bf16 v[72:75], v[166:169], v[214:217], v[72:75]
	v_mfma_f32_16x16x32_bf16 v[72:75], v[170:173], v[218:221], v[72:75]
	v_mfma_f32_16x16x32_bf16 v[68:71], v[174:177], v[214:217], v[68:71]
	v_mfma_f32_16x16x32_bf16 v[68:71], v[178:181], v[218:221], v[68:71]
	s_barrier
	s_setprio 0
	s_add_i32 s16, s55, s30
	v_lshl_add_u64 v[148:149], s[22:23], 0, v[134:135]
	s_mov_b32 m0, s16
	ds_read_b128 v[182:185], v153 offset:16384
	ds_read_b128 v[186:189], v153 offset:17408
	ds_read_b128 v[190:193], v153 offset:18432
	ds_read_b128 v[194:197], v153 offset:19456
	ds_read_b128 v[206:209], v153 offset:20480
	ds_read_b128 v[210:213], v153 offset:21504
	ds_read_b128 v[214:217], v153 offset:22528
	ds_read_b128 v[218:221], v153 offset:23552
	global_load_lds_dwordx4 v[148:149], off
	s_add_i32 m0, s16, 0x2000
	s_add_u32 s16, s22, 0x18000
	v_lshl_add_u64 v[198:199], s[22:23], 0, v[138:139]
	s_addc_u32 s17, s23, 0
	s_add_i32 s55, s59, s30
	global_load_lds_dwordx4 v[198:199], off
	v_lshl_add_u64 v[200:201], s[16:17], 0, v[134:135]
	s_mov_b32 m0, s55
	v_lshl_add_u64 v[222:223], s[24:25], 0, v[136:137]
	global_load_lds_dwordx4 v[200:201], off
	v_lshl_add_u64 v[200:201], s[16:17], 0, v[138:139]
	s_add_i32 m0, s55, 0x2000
	s_nop 0
	global_load_lds_dwordx4 v[200:201], off
	v_lshl_add_u64 v[200:201], s[24:25], 0, v[132:133]
	s_mov_b32 m0, s31
	s_nop 0
	global_load_lds_dwordx4 v[200:201], off
	s_mov_b32 m0, s34
	s_nop 0
	global_load_lds_dwordx4 v[222:223], off
	s_waitcnt vmcnt(8)
	s_waitcnt lgkmcnt(0)
	s_setprio 1
	s_barrier
	v_mfma_f32_16x16x32_bf16 v[64:67], v[144:147], v[182:185], v[64:67]
	v_mfma_f32_16x16x32_bf16 v[64:67], v[154:157], v[186:189], v[64:67]
	v_mfma_f32_16x16x32_bf16 v[60:63], v[158:161], v[182:185], v[60:63]
	v_mfma_f32_16x16x32_bf16 v[60:63], v[162:165], v[186:189], v[60:63]
	v_mfma_f32_16x16x32_bf16 v[48:51], v[144:147], v[190:193], v[48:51]
	v_mfma_f32_16x16x32_bf16 v[48:51], v[154:157], v[194:197], v[48:51]
	v_mfma_f32_16x16x32_bf16 v[44:47], v[158:161], v[190:193], v[44:47]
	v_mfma_f32_16x16x32_bf16 v[44:47], v[162:165], v[194:197], v[44:47]
	v_mfma_f32_16x16x32_bf16 v[30:33], v[144:147], v[206:209], v[30:33]
	v_mfma_f32_16x16x32_bf16 v[30:33], v[154:157], v[210:213], v[30:33]
	v_mfma_f32_16x16x32_bf16 v[26:29], v[158:161], v[206:209], v[26:29]
	v_mfma_f32_16x16x32_bf16 v[26:29], v[162:165], v[210:213], v[26:29]
	v_mfma_f32_16x16x32_bf16 v[14:17], v[144:147], v[214:217], v[14:17]
	v_mfma_f32_16x16x32_bf16 v[14:17], v[154:157], v[218:221], v[14:17]
	v_mfma_f32_16x16x32_bf16 v[10:13], v[158:161], v[214:217], v[10:13]
	v_mfma_f32_16x16x32_bf16 v[10:13], v[162:165], v[218:221], v[10:13]
	v_mfma_f32_16x16x32_bf16 v[56:59], v[166:169], v[182:185], v[56:59]
	v_mfma_f32_16x16x32_bf16 v[56:59], v[170:173], v[186:189], v[56:59]
	v_mfma_f32_16x16x32_bf16 v[52:55], v[174:177], v[182:185], v[52:55]
	v_mfma_f32_16x16x32_bf16 v[52:55], v[178:181], v[186:189], v[52:55]
	v_mfma_f32_16x16x32_bf16 v[40:43], v[166:169], v[190:193], v[40:43]
	v_mfma_f32_16x16x32_bf16 v[40:43], v[170:173], v[194:197], v[40:43]
	v_mfma_f32_16x16x32_bf16 v[36:39], v[174:177], v[190:193], v[36:39]
	v_mfma_f32_16x16x32_bf16 v[36:39], v[178:181], v[194:197], v[36:39]
	v_mfma_f32_16x16x32_bf16 v[22:25], v[166:169], v[206:209], v[22:25]
	v_mfma_f32_16x16x32_bf16 v[22:25], v[170:173], v[210:213], v[22:25]
	v_mfma_f32_16x16x32_bf16 v[18:21], v[174:177], v[206:209], v[18:21]
	v_mfma_f32_16x16x32_bf16 v[18:21], v[178:181], v[210:213], v[18:21]
	v_mfma_f32_16x16x32_bf16 v[6:9], v[166:169], v[214:217], v[6:9]
	v_mfma_f32_16x16x32_bf16 v[6:9], v[170:173], v[218:221], v[6:9]
	v_mfma_f32_16x16x32_bf16 v[2:5], v[174:177], v[214:217], v[2:5]
	v_mfma_f32_16x16x32_bf16 v[2:5], v[178:181], v[218:221], v[2:5]
	s_barrier
	s_setprio 0
	s_add_i32 s55, 0, 0x18000
	v_add_u32_e32 v34, s55, v152
	s_add_i32 s59, 0, 0x1c000
	ds_read_b128 v[144:147], v34
	ds_read_b128 v[154:157], v34 offset:1024
	ds_read_b128 v[158:161], v34 offset:2048
	ds_read_b128 v[162:165], v34 offset:3072
	v_add_u32_e32 v34, s59, v152
	ds_read_b128 v[166:169], v34
	ds_read_b128 v[170:173], v34 offset:1024
	ds_read_b128 v[174:177], v34 offset:2048
	ds_read_b128 v[178:181], v34 offset:3072
	s_add_u32 s16, s24, 0x18000
	s_addc_u32 s17, s25, 0
	s_mov_b32 m0, s35
	v_lshl_add_u64 v[224:225], s[16:17], 0, v[132:133]
	ds_read_b128 v[182:185], v153 offset:32768
	ds_read_b128 v[186:189], v153 offset:33792
	ds_read_b128 v[190:193], v153 offset:34816
	ds_read_b128 v[194:197], v153 offset:35840
	ds_read_b128 v[206:209], v153 offset:36864
	ds_read_b128 v[210:213], v153 offset:37888
	ds_read_b128 v[214:217], v153 offset:38912
	ds_read_b128 v[218:221], v153 offset:39936
	global_load_lds_dwordx4 v[224:225], off
	v_lshl_add_u64 v[224:225], s[16:17], 0, v[136:137]
	s_mov_b32 m0, s36
	s_nop 0
	global_load_lds_dwordx4 v[224:225], off
	s_waitcnt vmcnt(8)
	s_waitcnt lgkmcnt(0)
	s_setprio 1
	s_barrier
	v_mfma_f32_16x16x32_bf16 v[128:131], v[144:147], v[182:185], v[128:131]
	v_mfma_f32_16x16x32_bf16 v[128:131], v[154:157], v[186:189], v[128:131]
	v_mfma_f32_16x16x32_bf16 v[124:127], v[158:161], v[182:185], v[124:127]
	v_mfma_f32_16x16x32_bf16 v[124:127], v[162:165], v[186:189], v[124:127]
	v_mfma_f32_16x16x32_bf16 v[112:115], v[144:147], v[190:193], v[112:115]
	v_mfma_f32_16x16x32_bf16 v[112:115], v[154:157], v[194:197], v[112:115]
	v_mfma_f32_16x16x32_bf16 v[108:111], v[158:161], v[190:193], v[108:111]
	v_mfma_f32_16x16x32_bf16 v[108:111], v[162:165], v[194:197], v[108:111]
	v_mfma_f32_16x16x32_bf16 v[96:99], v[144:147], v[206:209], v[96:99]
	v_mfma_f32_16x16x32_bf16 v[96:99], v[154:157], v[210:213], v[96:99]
	v_mfma_f32_16x16x32_bf16 v[92:95], v[158:161], v[206:209], v[92:95]
	v_mfma_f32_16x16x32_bf16 v[92:95], v[162:165], v[210:213], v[92:95]
	v_mfma_f32_16x16x32_bf16 v[80:83], v[144:147], v[214:217], v[80:83]
	v_mfma_f32_16x16x32_bf16 v[80:83], v[154:157], v[218:221], v[80:83]
	v_mfma_f32_16x16x32_bf16 v[76:79], v[158:161], v[214:217], v[76:79]
	v_mfma_f32_16x16x32_bf16 v[76:79], v[162:165], v[218:221], v[76:79]
	v_mfma_f32_16x16x32_bf16 v[120:123], v[166:169], v[182:185], v[120:123]
	v_mfma_f32_16x16x32_bf16 v[120:123], v[170:173], v[186:189], v[120:123]
	v_mfma_f32_16x16x32_bf16 v[116:119], v[174:177], v[182:185], v[116:119]
	v_mfma_f32_16x16x32_bf16 v[116:119], v[178:181], v[186:189], v[116:119]
	v_mfma_f32_16x16x32_bf16 v[104:107], v[166:169], v[190:193], v[104:107]
	v_mfma_f32_16x16x32_bf16 v[104:107], v[170:173], v[194:197], v[104:107]
	v_mfma_f32_16x16x32_bf16 v[100:103], v[174:177], v[190:193], v[100:103]
	v_mfma_f32_16x16x32_bf16 v[100:103], v[178:181], v[194:197], v[100:103]
	v_mfma_f32_16x16x32_bf16 v[88:91], v[166:169], v[206:209], v[88:91]
	v_mfma_f32_16x16x32_bf16 v[88:91], v[170:173], v[210:213], v[88:91]
	v_mfma_f32_16x16x32_bf16 v[84:87], v[174:177], v[206:209], v[84:87]
	v_mfma_f32_16x16x32_bf16 v[84:87], v[178:181], v[210:213], v[84:87]
	v_mfma_f32_16x16x32_bf16 v[72:75], v[166:169], v[214:217], v[72:75]
	v_mfma_f32_16x16x32_bf16 v[72:75], v[170:173], v[218:221], v[72:75]
	v_mfma_f32_16x16x32_bf16 v[68:71], v[174:177], v[214:217], v[68:71]
	v_mfma_f32_16x16x32_bf16 v[68:71], v[178:181], v[218:221], v[68:71]
	s_barrier
	s_setprio 0
	s_add_i32 s16, s55, s30
	v_lshl_add_u64 v[148:149], v[148:149], 0, s[18:19]
	s_mov_b32 m0, s16
	ds_read_b128 v[182:185], v153 offset:49152
	ds_read_b128 v[186:189], v153 offset:50176
	ds_read_b128 v[190:193], v153 offset:51200
	ds_read_b128 v[194:197], v153 offset:52224
	ds_read_b128 v[206:209], v153 offset:53248
	ds_read_b128 v[210:213], v153 offset:54272
	ds_read_b128 v[214:217], v153 offset:55296
	ds_read_b128 v[218:221], v153 offset:56320
	global_load_lds_dwordx4 v[148:149], off
	s_add_i32 m0, s16, 0x2000
	s_add_u32 s16, s22, 0x18080
	v_lshl_add_u64 v[148:149], v[198:199], 0, s[18:19]
	s_addc_u32 s17, s23, 0
	s_add_i32 s22, s59, s30
	global_load_lds_dwordx4 v[148:149], off
	v_lshl_add_u64 v[148:149], s[16:17], 0, v[134:135]
	s_mov_b32 m0, s22
	s_nop 0
	global_load_lds_dwordx4 v[148:149], off
	v_lshl_add_u64 v[148:149], s[16:17], 0, v[138:139]
	s_add_i32 m0, s22, 0x2000
	s_nop 0
	global_load_lds_dwordx4 v[148:149], off
	v_lshl_add_u64 v[148:149], v[200:201], 0, s[18:19]
	s_mov_b32 m0, s37
	s_nop 0
	global_load_lds_dwordx4 v[148:149], off
	v_lshl_add_u64 v[148:149], v[222:223], 0, s[18:19]
	s_mov_b32 m0, s38
	s_nop 0
	global_load_lds_dwordx4 v[148:149], off
	s_waitcnt vmcnt(8)
	s_waitcnt lgkmcnt(0)
	s_setprio 1
	s_barrier
	v_mfma_f32_16x16x32_bf16 v[64:67], v[144:147], v[182:185], v[64:67]
	v_mfma_f32_16x16x32_bf16 v[64:67], v[154:157], v[186:189], v[64:67]
	v_mfma_f32_16x16x32_bf16 v[60:63], v[158:161], v[182:185], v[60:63]
	v_mfma_f32_16x16x32_bf16 v[60:63], v[162:165], v[186:189], v[60:63]
	v_mfma_f32_16x16x32_bf16 v[48:51], v[144:147], v[190:193], v[48:51]
	v_mfma_f32_16x16x32_bf16 v[48:51], v[154:157], v[194:197], v[48:51]
	v_mfma_f32_16x16x32_bf16 v[44:47], v[158:161], v[190:193], v[44:47]
	v_mfma_f32_16x16x32_bf16 v[44:47], v[162:165], v[194:197], v[44:47]
	v_mfma_f32_16x16x32_bf16 v[30:33], v[144:147], v[206:209], v[30:33]
	v_mfma_f32_16x16x32_bf16 v[30:33], v[154:157], v[210:213], v[30:33]
	v_mfma_f32_16x16x32_bf16 v[26:29], v[158:161], v[206:209], v[26:29]
	v_mfma_f32_16x16x32_bf16 v[26:29], v[162:165], v[210:213], v[26:29]
	v_mfma_f32_16x16x32_bf16 v[14:17], v[144:147], v[214:217], v[14:17]
	v_mfma_f32_16x16x32_bf16 v[14:17], v[154:157], v[218:221], v[14:17]
	v_mfma_f32_16x16x32_bf16 v[10:13], v[158:161], v[214:217], v[10:13]
	v_mfma_f32_16x16x32_bf16 v[10:13], v[162:165], v[218:221], v[10:13]
	v_mfma_f32_16x16x32_bf16 v[56:59], v[166:169], v[182:185], v[56:59]
	v_mfma_f32_16x16x32_bf16 v[56:59], v[170:173], v[186:189], v[56:59]
	v_mfma_f32_16x16x32_bf16 v[52:55], v[174:177], v[182:185], v[52:55]
	v_mfma_f32_16x16x32_bf16 v[52:55], v[178:181], v[186:189], v[52:55]
	v_mfma_f32_16x16x32_bf16 v[40:43], v[166:169], v[190:193], v[40:43]
	v_mfma_f32_16x16x32_bf16 v[40:43], v[170:173], v[194:197], v[40:43]
	v_mfma_f32_16x16x32_bf16 v[36:39], v[174:177], v[190:193], v[36:39]
	v_mfma_f32_16x16x32_bf16 v[36:39], v[178:181], v[194:197], v[36:39]
	v_mfma_f32_16x16x32_bf16 v[22:25], v[166:169], v[206:209], v[22:25]
	v_mfma_f32_16x16x32_bf16 v[22:25], v[170:173], v[210:213], v[22:25]
	v_mfma_f32_16x16x32_bf16 v[18:21], v[174:177], v[206:209], v[18:21]
	v_mfma_f32_16x16x32_bf16 v[18:21], v[178:181], v[210:213], v[18:21]
	v_mfma_f32_16x16x32_bf16 v[6:9], v[166:169], v[214:217], v[6:9]
	v_mfma_f32_16x16x32_bf16 v[6:9], v[170:173], v[218:221], v[6:9]
	v_mfma_f32_16x16x32_bf16 v[2:5], v[174:177], v[214:217], v[2:5]
	v_mfma_f32_16x16x32_bf16 v[2:5], v[178:181], v[218:221], v[2:5]
	s_barrier
	s_setprio 0
	s_add_i32 s54, s54, 2
	s_add_u32 s44, s44, 0x100
	s_addc_u32 s45, s45, 0
	s_cmp_gt_u32 s54, 3
	s_mov_b64 s[16:17], s[20:21]
	s_cbranch_scc0 .LBB0_1391
	s_and_b64 vcc, exec, s[10:11]
	s_cbranch_vccz .LBB0_1394
	s_barrier

.LBB0_1517:
	s_add_u32 s36, s34, 0xfffc0080
	s_addc_u32 s37, s35, -1
	s_add_i32 s63, 0, 0x10000
	s_cmp_eq_u32 s62, 12
	s_cselect_b32 s43, s15, s37
	s_cselect_b32 s42, s17, s36
	s_cselect_b32 s37, s25, s61
	s_cselect_b32 s36, s27, s60
	s_add_i32 s66, 0, 0x14000
	v_add_u32_e32 v144, s63, v174
	v_add_u32_e32 v170, s66, v174
	ds_read_b128 v[132:135], v144
	ds_read_b128 v[136:139], v144 offset:1024
	ds_read_b128 v[140:143], v144 offset:2048
	ds_read_b128 v[144:147], v144 offset:3072
	ds_read_b128 v[158:161], v170
	ds_read_b128 v[162:165], v170 offset:1024
	ds_read_b128 v[166:169], v170 offset:2048
	ds_read_b128 v[176:179], v170 offset:3072
	v_lshl_add_u64 v[170:171], s[34:35], 0, v[154:155]
	s_add_i32 m0, s45, 0xc000
	ds_read_b128 v[180:183], v175
	ds_read_b128 v[184:187], v175 offset:1024
	ds_read_b128 v[188:191], v175 offset:2048
	ds_read_b128 v[192:195], v175 offset:3072
	ds_read_b128 v[206:209], v175 offset:4096
	ds_read_b128 v[210:213], v175 offset:5120
	ds_read_b128 v[214:217], v175 offset:6144
	ds_read_b128 v[218:221], v175 offset:7168
	global_load_lds_dwordx4 v[170:171], off
	v_lshl_add_u64 v[170:171], s[34:35], 0, v[156:157]
	s_add_i32 m0, s45, 0xe000
	s_nop 0
	global_load_lds_dwordx4 v[170:171], off
	s_waitcnt vmcnt(8)
	s_waitcnt lgkmcnt(0)
	s_setprio 1
	s_barrier
	v_mfma_f32_16x16x32_bf16 v[128:131], v[132:135], v[180:183], v[128:131]
	v_mfma_f32_16x16x32_bf16 v[128:131], v[136:139], v[184:187], v[128:131]
	v_mfma_f32_16x16x32_bf16 v[124:127], v[140:143], v[180:183], v[124:127]
	v_mfma_f32_16x16x32_bf16 v[124:127], v[144:147], v[184:187], v[124:127]
	v_mfma_f32_16x16x32_bf16 v[112:115], v[132:135], v[188:191], v[112:115]
	v_mfma_f32_16x16x32_bf16 v[112:115], v[136:139], v[192:195], v[112:115]
	v_mfma_f32_16x16x32_bf16 v[108:111], v[140:143], v[188:191], v[108:111]
	v_mfma_f32_16x16x32_bf16 v[108:111], v[144:147], v[192:195], v[108:111]
	v_mfma_f32_16x16x32_bf16 v[96:99], v[132:135], v[206:209], v[96:99]
	v_mfma_f32_16x16x32_bf16 v[96:99], v[136:139], v[210:213], v[96:99]
	v_mfma_f32_16x16x32_bf16 v[92:95], v[140:143], v[206:209], v[92:95]
	v_mfma_f32_16x16x32_bf16 v[92:95], v[144:147], v[210:213], v[92:95]
	v_mfma_f32_16x16x32_bf16 v[80:83], v[132:135], v[214:217], v[80:83]
	v_mfma_f32_16x16x32_bf16 v[80:83], v[136:139], v[218:221], v[80:83]
	v_mfma_f32_16x16x32_bf16 v[76:79], v[140:143], v[214:217], v[76:79]
	v_mfma_f32_16x16x32_bf16 v[76:79], v[144:147], v[218:221], v[76:79]
	v_mfma_f32_16x16x32_bf16 v[120:123], v[158:161], v[180:183], v[120:123]
	v_mfma_f32_16x16x32_bf16 v[120:123], v[162:165], v[184:187], v[120:123]
	v_mfma_f32_16x16x32_bf16 v[116:119], v[166:169], v[180:183], v[116:119]
	v_mfma_f32_16x16x32_bf16 v[116:119], v[176:179], v[184:187], v[116:119]
	v_mfma_f32_16x16x32_bf16 v[104:107], v[158:161], v[188:191], v[104:107]
	v_mfma_f32_16x16x32_bf16 v[104:107], v[162:165], v[192:195], v[104:107]
	v_mfma_f32_16x16x32_bf16 v[100:103], v[166:169], v[188:191], v[100:103]
	v_mfma_f32_16x16x32_bf16 v[100:103], v[176:179], v[192:195], v[100:103]
	v_mfma_f32_16x16x32_bf16 v[88:91], v[158:161], v[206:209], v[88:91]
	v_mfma_f32_16x16x32_bf16 v[88:91], v[162:165], v[210:213], v[88:91]
	v_mfma_f32_16x16x32_bf16 v[84:87], v[166:169], v[206:209], v[84:87]
	v_mfma_f32_16x16x32_bf16 v[84:87], v[176:179], v[210:213], v[84:87]
	v_mfma_f32_16x16x32_bf16 v[72:75], v[158:161], v[214:217], v[72:75]
	v_mfma_f32_16x16x32_bf16 v[72:75], v[162:165], v[218:221], v[72:75]
	v_mfma_f32_16x16x32_bf16 v[68:71], v[166:169], v[214:217], v[68:71]
	v_mfma_f32_16x16x32_bf16 v[68:71], v[176:179], v[218:221], v[68:71]
	s_barrier
	s_setprio 0
	s_add_i32 s63, s63, s44
	v_lshl_add_u64 v[170:171], s[36:37], 0, v[34:35]
	s_mov_b32 m0, s63
	ds_read_b128 v[180:183], v175 offset:16384
	ds_read_b128 v[184:187], v175 offset:17408
	ds_read_b128 v[188:191], v175 offset:18432
	ds_read_b128 v[192:195], v175 offset:19456
	ds_read_b128 v[206:209], v175 offset:20480
	ds_read_b128 v[210:213], v175 offset:21504
	ds_read_b128 v[214:217], v175 offset:22528
	ds_read_b128 v[218:221], v175 offset:23552
	global_load_lds_dwordx4 v[170:171], off
	s_add_i32 m0, s63, 0x2000
	s_add_u32 s64, s36, 0x40000
	v_lshl_add_u64 v[196:197], s[36:37], 0, v[152:153]
	s_addc_u32 s65, s37, 0
	s_add_i32 s63, s66, s44
	global_load_lds_dwordx4 v[196:197], off
	v_lshl_add_u64 v[198:199], s[64:65], 0, v[34:35]
	s_mov_b32 m0, s63
	v_lshl_add_u64 v[200:201], s[42:43], 0, v[150:151]
	global_load_lds_dwordx4 v[198:199], off
	v_lshl_add_u64 v[198:199], s[64:65], 0, v[152:153]
	s_add_i32 m0, s63, 0x2000
	s_nop 0
	global_load_lds_dwordx4 v[198:199], off
	v_lshl_add_u64 v[198:199], s[42:43], 0, v[148:149]
	s_mov_b32 m0, s45
	s_nop 0
	global_load_lds_dwordx4 v[198:199], off
	s_mov_b32 m0, s46
	s_nop 0
	global_load_lds_dwordx4 v[200:201], off
	s_waitcnt vmcnt(8)
	s_waitcnt lgkmcnt(0)
	s_setprio 1
	s_barrier
	v_mfma_f32_16x16x32_bf16 v[64:67], v[132:135], v[180:183], v[64:67]
	v_mfma_f32_16x16x32_bf16 v[64:67], v[136:139], v[184:187], v[64:67]
	v_mfma_f32_16x16x32_bf16 v[60:63], v[140:143], v[180:183], v[60:63]
	v_mfma_f32_16x16x32_bf16 v[60:63], v[144:147], v[184:187], v[60:63]
	v_mfma_f32_16x16x32_bf16 v[48:51], v[132:135], v[188:191], v[48:51]
	v_mfma_f32_16x16x32_bf16 v[48:51], v[136:139], v[192:195], v[48:51]
	v_mfma_f32_16x16x32_bf16 v[44:47], v[140:143], v[188:191], v[44:47]
	v_mfma_f32_16x16x32_bf16 v[44:47], v[144:147], v[192:195], v[44:47]
	v_mfma_f32_16x16x32_bf16 v[30:33], v[132:135], v[206:209], v[30:33]
	v_mfma_f32_16x16x32_bf16 v[30:33], v[136:139], v[210:213], v[30:33]
	v_mfma_f32_16x16x32_bf16 v[26:29], v[140:143], v[206:209], v[26:29]
	v_mfma_f32_16x16x32_bf16 v[26:29], v[144:147], v[210:213], v[26:29]
	v_mfma_f32_16x16x32_bf16 v[14:17], v[132:135], v[214:217], v[14:17]
	v_mfma_f32_16x16x32_bf16 v[14:17], v[136:139], v[218:221], v[14:17]
	v_mfma_f32_16x16x32_bf16 v[10:13], v[140:143], v[214:217], v[10:13]
	v_mfma_f32_16x16x32_bf16 v[10:13], v[144:147], v[218:221], v[10:13]
	v_mfma_f32_16x16x32_bf16 v[56:59], v[158:161], v[180:183], v[56:59]
	v_mfma_f32_16x16x32_bf16 v[56:59], v[162:165], v[184:187], v[56:59]
	v_mfma_f32_16x16x32_bf16 v[52:55], v[166:169], v[180:183], v[52:55]
	v_mfma_f32_16x16x32_bf16 v[52:55], v[176:179], v[184:187], v[52:55]
	v_mfma_f32_16x16x32_bf16 v[40:43], v[158:161], v[188:191], v[40:43]
	v_mfma_f32_16x16x32_bf16 v[40:43], v[162:165], v[192:195], v[40:43]
	v_mfma_f32_16x16x32_bf16 v[36:39], v[166:169], v[188:191], v[36:39]
	v_mfma_f32_16x16x32_bf16 v[36:39], v[176:179], v[192:195], v[36:39]
	v_mfma_f32_16x16x32_bf16 v[22:25], v[158:161], v[206:209], v[22:25]
	v_mfma_f32_16x16x32_bf16 v[22:25], v[162:165], v[210:213], v[22:25]
	v_mfma_f32_16x16x32_bf16 v[18:21], v[166:169], v[206:209], v[18:21]
	v_mfma_f32_16x16x32_bf16 v[18:21], v[176:179], v[210:213], v[18:21]
	v_mfma_f32_16x16x32_bf16 v[6:9], v[158:161], v[214:217], v[6:9]
	v_mfma_f32_16x16x32_bf16 v[6:9], v[162:165], v[218:221], v[6:9]
	v_mfma_f32_16x16x32_bf16 v[2:5], v[166:169], v[214:217], v[2:5]
	v_mfma_f32_16x16x32_bf16 v[2:5], v[176:179], v[218:221], v[2:5]
	s_barrier
	s_setprio 0
	s_add_i32 s63, 0, 0x18000
	s_add_i32 s64, 0, 0x1c000
	v_add_u32_e32 v144, s63, v174
	v_add_u32_e32 v176, s64, v174
	ds_read_b128 v[132:135], v144
	ds_read_b128 v[136:139], v144 offset:1024
	ds_read_b128 v[140:143], v144 offset:2048
	ds_read_b128 v[144:147], v144 offset:3072
	ds_read_b128 v[158:161], v176
	ds_read_b128 v[162:165], v176 offset:1024
	ds_read_b128 v[166:169], v176 offset:2048
	ds_read_b128 v[176:179], v176 offset:3072
	s_add_u32 s42, s42, 0x40000
	s_addc_u32 s43, s43, 0
	s_mov_b32 m0, s47
	v_lshl_add_u64 v[222:223], s[42:43], 0, v[148:149]
	ds_read_b128 v[180:183], v175 offset:32768
	ds_read_b128 v[184:187], v175 offset:33792
	ds_read_b128 v[188:191], v175 offset:34816
	ds_read_b128 v[192:195], v175 offset:35840
	ds_read_b128 v[206:209], v175 offset:36864
	ds_read_b128 v[210:213], v175 offset:37888
	ds_read_b128 v[214:217], v175 offset:38912
	ds_read_b128 v[218:221], v175 offset:39936
	global_load_lds_dwordx4 v[222:223], off
	v_lshl_add_u64 v[222:223], s[42:43], 0, v[150:151]
	s_mov_b32 m0, s52
	s_nop 0
	global_load_lds_dwordx4 v[222:223], off
	s_waitcnt vmcnt(8)
	s_waitcnt lgkmcnt(0)
	s_setprio 1
	s_barrier
	v_mfma_f32_16x16x32_bf16 v[128:131], v[132:135], v[180:183], v[128:131]
	v_mfma_f32_16x16x32_bf16 v[128:131], v[136:139], v[184:187], v[128:131]
	v_mfma_f32_16x16x32_bf16 v[124:127], v[140:143], v[180:183], v[124:127]
	v_mfma_f32_16x16x32_bf16 v[124:127], v[144:147], v[184:187], v[124:127]
	v_mfma_f32_16x16x32_bf16 v[112:115], v[132:135], v[188:191], v[112:115]
	v_mfma_f32_16x16x32_bf16 v[112:115], v[136:139], v[192:195], v[112:115]
	v_mfma_f32_16x16x32_bf16 v[108:111], v[140:143], v[188:191], v[108:111]
	v_mfma_f32_16x16x32_bf16 v[108:111], v[144:147], v[192:195], v[108:111]
	v_mfma_f32_16x16x32_bf16 v[96:99], v[132:135], v[206:209], v[96:99]
	v_mfma_f32_16x16x32_bf16 v[96:99], v[136:139], v[210:213], v[96:99]
	v_mfma_f32_16x16x32_bf16 v[92:95], v[140:143], v[206:209], v[92:95]
	v_mfma_f32_16x16x32_bf16 v[92:95], v[144:147], v[210:213], v[92:95]
	v_mfma_f32_16x16x32_bf16 v[80:83], v[132:135], v[214:217], v[80:83]
	v_mfma_f32_16x16x32_bf16 v[80:83], v[136:139], v[218:221], v[80:83]
	v_mfma_f32_16x16x32_bf16 v[76:79], v[140:143], v[214:217], v[76:79]
	v_mfma_f32_16x16x32_bf16 v[76:79], v[144:147], v[218:221], v[76:79]
	v_mfma_f32_16x16x32_bf16 v[120:123], v[158:161], v[180:183], v[120:123]
	v_mfma_f32_16x16x32_bf16 v[120:123], v[162:165], v[184:187], v[120:123]
	v_mfma_f32_16x16x32_bf16 v[116:119], v[166:169], v[180:183], v[116:119]
	v_mfma_f32_16x16x32_bf16 v[116:119], v[176:179], v[184:187], v[116:119]
	v_mfma_f32_16x16x32_bf16 v[104:107], v[158:161], v[188:191], v[104:107]
	v_mfma_f32_16x16x32_bf16 v[104:107], v[162:165], v[192:195], v[104:107]
	v_mfma_f32_16x16x32_bf16 v[100:103], v[166:169], v[188:191], v[100:103]
	v_mfma_f32_16x16x32_bf16 v[100:103], v[176:179], v[192:195], v[100:103]
	v_mfma_f32_16x16x32_bf16 v[88:91], v[158:161], v[206:209], v[88:91]
	v_mfma_f32_16x16x32_bf16 v[88:91], v[162:165], v[210:213], v[88:91]
	v_mfma_f32_16x16x32_bf16 v[84:87], v[166:169], v[206:209], v[84:87]
	v_mfma_f32_16x16x32_bf16 v[84:87], v[176:179], v[210:213], v[84:87]
	v_mfma_f32_16x16x32_bf16 v[72:75], v[158:161], v[214:217], v[72:75]
	v_mfma_f32_16x16x32_bf16 v[72:75], v[162:165], v[218:221], v[72:75]
	v_mfma_f32_16x16x32_bf16 v[68:71], v[166:169], v[214:217], v[68:71]
	v_mfma_f32_16x16x32_bf16 v[68:71], v[176:179], v[218:221], v[68:71]
	s_barrier
	s_setprio 0
	s_add_i32 s42, s63, s44
	v_lshl_add_u64 v[170:171], v[170:171], 0, s[18:19]
	s_mov_b32 m0, s42
	ds_read_b128 v[180:183], v175 offset:49152
	ds_read_b128 v[184:187], v175 offset:50176
	ds_read_b128 v[188:191], v175 offset:51200
	ds_read_b128 v[192:195], v175 offset:52224
	ds_read_b128 v[206:209], v175 offset:53248
	ds_read_b128 v[210:213], v175 offset:54272
	ds_read_b128 v[214:217], v175 offset:55296
	ds_read_b128 v[218:221], v175 offset:56320
	global_load_lds_dwordx4 v[170:171], off
	s_add_i32 m0, s42, 0x2000
	s_add_u32 s36, s36, 0x40080
	v_lshl_add_u64 v[170:171], v[196:197], 0, s[18:19]
	s_addc_u32 s37, s37, 0
	s_add_i32 s42, s64, s44
	global_load_lds_dwordx4 v[170:171], off
	v_lshl_add_u64 v[170:171], s[36:37], 0, v[34:35]
	s_mov_b32 m0, s42
	s_nop 0
	global_load_lds_dwordx4 v[170:171], off
	v_lshl_add_u64 v[170:171], s[36:37], 0, v[152:153]
	s_add_i32 m0, s42, 0x2000
	s_nop 0
	global_load_lds_dwordx4 v[170:171], off
	v_lshl_add_u64 v[170:171], v[198:199], 0, s[18:19]
	s_mov_b32 m0, s54
	s_nop 0
	global_load_lds_dwordx4 v[170:171], off
	v_lshl_add_u64 v[170:171], v[200:201], 0, s[18:19]
	s_mov_b32 m0, s55
	s_nop 0
	global_load_lds_dwordx4 v[170:171], off
	s_waitcnt vmcnt(8)
	s_waitcnt lgkmcnt(0)
	s_setprio 1
	s_barrier
	v_mfma_f32_16x16x32_bf16 v[64:67], v[132:135], v[180:183], v[64:67]
	v_mfma_f32_16x16x32_bf16 v[64:67], v[136:139], v[184:187], v[64:67]
	v_mfma_f32_16x16x32_bf16 v[60:63], v[140:143], v[180:183], v[60:63]
	v_mfma_f32_16x16x32_bf16 v[60:63], v[144:147], v[184:187], v[60:63]
	v_mfma_f32_16x16x32_bf16 v[48:51], v[132:135], v[188:191], v[48:51]
	v_mfma_f32_16x16x32_bf16 v[48:51], v[136:139], v[192:195], v[48:51]
	v_mfma_f32_16x16x32_bf16 v[44:47], v[140:143], v[188:191], v[44:47]
	v_mfma_f32_16x16x32_bf16 v[44:47], v[144:147], v[192:195], v[44:47]
	v_mfma_f32_16x16x32_bf16 v[30:33], v[132:135], v[206:209], v[30:33]
	v_mfma_f32_16x16x32_bf16 v[30:33], v[136:139], v[210:213], v[30:33]
	v_mfma_f32_16x16x32_bf16 v[26:29], v[140:143], v[206:209], v[26:29]
	v_mfma_f32_16x16x32_bf16 v[26:29], v[144:147], v[210:213], v[26:29]
	v_mfma_f32_16x16x32_bf16 v[14:17], v[132:135], v[214:217], v[14:17]
	v_mfma_f32_16x16x32_bf16 v[14:17], v[136:139], v[218:221], v[14:17]
	v_mfma_f32_16x16x32_bf16 v[10:13], v[140:143], v[214:217], v[10:13]
	v_mfma_f32_16x16x32_bf16 v[10:13], v[144:147], v[218:221], v[10:13]
	v_mfma_f32_16x16x32_bf16 v[56:59], v[158:161], v[180:183], v[56:59]
	v_mfma_f32_16x16x32_bf16 v[56:59], v[162:165], v[184:187], v[56:59]
	v_mfma_f32_16x16x32_bf16 v[52:55], v[166:169], v[180:183], v[52:55]
	v_mfma_f32_16x16x32_bf16 v[52:55], v[176:179], v[184:187], v[52:55]
	v_mfma_f32_16x16x32_bf16 v[40:43], v[158:161], v[188:191], v[40:43]
	v_mfma_f32_16x16x32_bf16 v[40:43], v[162:165], v[192:195], v[40:43]
	v_mfma_f32_16x16x32_bf16 v[36:39], v[166:169], v[188:191], v[36:39]
	v_mfma_f32_16x16x32_bf16 v[36:39], v[176:179], v[192:195], v[36:39]
	v_mfma_f32_16x16x32_bf16 v[22:25], v[158:161], v[206:209], v[22:25]
	v_mfma_f32_16x16x32_bf16 v[22:25], v[162:165], v[210:213], v[22:25]
	v_mfma_f32_16x16x32_bf16 v[18:21], v[166:169], v[206:209], v[18:21]
	v_mfma_f32_16x16x32_bf16 v[18:21], v[176:179], v[210:213], v[18:21]
	v_mfma_f32_16x16x32_bf16 v[6:9], v[158:161], v[214:217], v[6:9]
	v_mfma_f32_16x16x32_bf16 v[6:9], v[162:165], v[218:221], v[6:9]
	v_mfma_f32_16x16x32_bf16 v[2:5], v[166:169], v[214:217], v[2:5]
	v_mfma_f32_16x16x32_bf16 v[2:5], v[176:179], v[218:221], v[2:5]
	s_barrier
	s_setprio 0
	s_add_i32 s62, s62, 2
	s_add_u32 s34, s34, 0x100
	s_addc_u32 s35, s35, 0
	s_add_u32 s60, s60, 0x100
	s_addc_u32 s61, s61, 0
	s_cmp_gt_u32 s62, 13
	s_cbranch_scc0 .LBB0_1517
	s_and_b64 vcc, exec, s[22:23]
	s_cbranch_vccz .LBB0_1520
	s_barrier

.LBB0_1643:
	v_mfma_f32_16x16x32_bf16 v[130:133], v[150:153], v[190:193], v[130:133]
	v_mfma_f32_16x16x32_bf16 v[130:133], v[154:157], v[194:197], v[130:133]
	v_mfma_f32_16x16x32_bf16 v[126:129], v[158:161], v[190:193], v[126:129]
	v_mfma_f32_16x16x32_bf16 v[126:129], v[162:165], v[194:197], v[126:129]
	v_mfma_f32_16x16x32_bf16 v[114:117], v[150:153], v[182:185], v[114:117]
	v_mfma_f32_16x16x32_bf16 v[114:117], v[154:157], v[186:189], v[114:117]
	v_mfma_f32_16x16x32_bf16 v[110:113], v[158:161], v[182:185], v[110:113]
	v_mfma_f32_16x16x32_bf16 v[110:113], v[162:165], v[186:189], v[110:113]
	v_mfma_f32_16x16x32_bf16 v[98:101], v[150:153], v[174:177], v[98:101]
	v_mfma_f32_16x16x32_bf16 v[98:101], v[154:157], v[178:181], v[98:101]
	v_mfma_f32_16x16x32_bf16 v[94:97], v[158:161], v[174:177], v[94:97]
	v_mfma_f32_16x16x32_bf16 v[94:97], v[162:165], v[178:181], v[94:97]
	v_mfma_f32_16x16x32_bf16 v[82:85], v[150:153], v[166:169], v[82:85]
	v_mfma_f32_16x16x32_bf16 v[82:85], v[154:157], v[170:173], v[82:85]
	v_mfma_f32_16x16x32_bf16 v[78:81], v[158:161], v[166:169], v[78:81]
	v_mfma_f32_16x16x32_bf16 v[78:81], v[162:165], v[170:173], v[78:81]
	v_mfma_f32_16x16x32_bf16 v[122:125], v[134:137], v[190:193], v[122:125]
	v_mfma_f32_16x16x32_bf16 v[122:125], v[138:141], v[194:197], v[122:125]
	v_mfma_f32_16x16x32_bf16 v[118:121], v[142:145], v[190:193], v[118:121]
	v_mfma_f32_16x16x32_bf16 v[118:121], v[146:149], v[194:197], v[118:121]
	v_mfma_f32_16x16x32_bf16 v[106:109], v[134:137], v[182:185], v[106:109]
	v_mfma_f32_16x16x32_bf16 v[106:109], v[138:141], v[186:189], v[106:109]
	v_mfma_f32_16x16x32_bf16 v[102:105], v[142:145], v[182:185], v[102:105]
	v_mfma_f32_16x16x32_bf16 v[102:105], v[146:149], v[186:189], v[102:105]
	v_mfma_f32_16x16x32_bf16 v[90:93], v[134:137], v[174:177], v[90:93]
	v_mfma_f32_16x16x32_bf16 v[90:93], v[138:141], v[178:181], v[90:93]
	v_mfma_f32_16x16x32_bf16 v[86:89], v[142:145], v[174:177], v[86:89]
	v_mfma_f32_16x16x32_bf16 v[86:89], v[146:149], v[178:181], v[86:89]
	v_mfma_f32_16x16x32_bf16 v[74:77], v[134:137], v[166:169], v[74:77]
	v_mfma_f32_16x16x32_bf16 v[74:77], v[138:141], v[170:173], v[74:77]
	v_mfma_f32_16x16x32_bf16 v[70:73], v[142:145], v[166:169], v[70:73]
	v_mfma_f32_16x16x32_bf16 v[70:73], v[146:149], v[170:173], v[70:73]
	s_barrier
	s_setprio 0
	s_mov_b32 m0, s55
	v_lshl_add_u64 v[198:199], s[40:41], 0, v[210:211]
	s_add_u32 s78, s40, 0x80000
	ds_read_b128 v[166:169], v244 offset:16384
	ds_read_b128 v[170:173], v244 offset:17408
	ds_read_b128 v[174:177], v244 offset:18432
	ds_read_b128 v[178:181], v244 offset:19456
	ds_read_b128 v[182:185], v244 offset:20480
	ds_read_b128 v[186:189], v244 offset:21504
	ds_read_b128 v[190:193], v244 offset:22528
	ds_read_b128 v[194:197], v244 offset:23552
	global_load_lds_dwordx4 v[198:199], off
	v_lshl_add_u64 v[200:201], s[40:41], 0, v[214:215]
	s_mov_b32 m0, s59
	s_addc_u32 s79, s41, 0
	global_load_lds_dwordx4 v[200:201], off
	v_lshl_add_u64 v[36:37], s[78:79], 0, v[210:211]
	s_mov_b32 m0, s60
	v_lshl_add_u64 v[246:247], s[42:43], 0, v[208:209]
	global_load_lds_dwordx4 v[36:37], off
	v_lshl_add_u64 v[36:37], s[78:79], 0, v[214:215]
	s_mov_b32 m0, s61
	v_lshl_add_u64 v[248:249], s[42:43], 0, v[212:213]
	global_load_lds_dwordx4 v[36:37], off
	s_mov_b32 m0, s54
	s_nop 0
	global_load_lds_dwordx4 v[246:247], off
	s_mov_b32 m0, s62
	s_nop 0
	global_load_lds_dwordx4 v[248:249], off
	s_waitcnt vmcnt(8)
	s_waitcnt lgkmcnt(0)
	s_setprio 1
	s_barrier
	v_mfma_f32_16x16x32_bf16 v[66:69], v[150:153], v[166:169], v[66:69]
	v_mfma_f32_16x16x32_bf16 v[66:69], v[154:157], v[170:173], v[66:69]
	v_mfma_f32_16x16x32_bf16 v[62:65], v[158:161], v[166:169], v[62:65]
	v_mfma_f32_16x16x32_bf16 v[62:65], v[162:165], v[170:173], v[62:65]
	v_mfma_f32_16x16x32_bf16 v[50:53], v[150:153], v[174:177], v[50:53]
	v_mfma_f32_16x16x32_bf16 v[50:53], v[154:157], v[178:181], v[50:53]
	v_mfma_f32_16x16x32_bf16 v[46:49], v[158:161], v[174:177], v[46:49]
	v_mfma_f32_16x16x32_bf16 v[46:49], v[162:165], v[178:181], v[46:49]
	v_mfma_f32_16x16x32_bf16 v[30:33], v[150:153], v[182:185], v[30:33]
	v_mfma_f32_16x16x32_bf16 v[30:33], v[154:157], v[186:189], v[30:33]
	v_mfma_f32_16x16x32_bf16 v[26:29], v[158:161], v[182:185], v[26:29]
	v_mfma_f32_16x16x32_bf16 v[26:29], v[162:165], v[186:189], v[26:29]
	v_mfma_f32_16x16x32_bf16 v[14:17], v[150:153], v[190:193], v[14:17]
	v_mfma_f32_16x16x32_bf16 v[14:17], v[154:157], v[194:197], v[14:17]
	v_mfma_f32_16x16x32_bf16 v[10:13], v[158:161], v[190:193], v[10:13]
	v_mfma_f32_16x16x32_bf16 v[10:13], v[162:165], v[194:197], v[10:13]
	v_mfma_f32_16x16x32_bf16 v[58:61], v[134:137], v[166:169], v[58:61]
	v_mfma_f32_16x16x32_bf16 v[58:61], v[138:141], v[170:173], v[58:61]
	v_mfma_f32_16x16x32_bf16 v[54:57], v[142:145], v[166:169], v[54:57]
	v_mfma_f32_16x16x32_bf16 v[54:57], v[146:149], v[170:173], v[54:57]
	v_mfma_f32_16x16x32_bf16 v[42:45], v[134:137], v[174:177], v[42:45]
	v_mfma_f32_16x16x32_bf16 v[42:45], v[138:141], v[178:181], v[42:45]
	v_mfma_f32_16x16x32_bf16 v[36:39], v[142:145], v[174:177], v[38:41]
	v_mfma_f32_16x16x32_bf16 v[36:39], v[146:149], v[178:181], v[36:39]
	v_mfma_f32_16x16x32_bf16 v[22:25], v[134:137], v[182:185], v[22:25]
	v_mfma_f32_16x16x32_bf16 v[22:25], v[138:141], v[186:189], v[22:25]
	v_mfma_f32_16x16x32_bf16 v[18:21], v[142:145], v[182:185], v[18:21]
	v_mfma_f32_16x16x32_bf16 v[18:21], v[146:149], v[186:189], v[18:21]
	v_mfma_f32_16x16x32_bf16 v[6:9], v[134:137], v[190:193], v[6:9]
	v_mfma_f32_16x16x32_bf16 v[6:9], v[138:141], v[194:197], v[6:9]
	v_mfma_f32_16x16x32_bf16 v[2:5], v[142:145], v[190:193], v[2:5]
	v_mfma_f32_16x16x32_bf16 v[2:5], v[146:149], v[194:197], v[2:5]
	s_barrier
	s_setprio 0
	s_add_i32 s78, 0, 0x18000
	v_add_u32_e32 v34, s78, v242
	s_add_i32 s79, 0, 0x1c000
	ds_read_b128 v[134:137], v34
	ds_read_b128 v[138:141], v34 offset:1024
	ds_read_b128 v[142:145], v34 offset:2048
	ds_read_b128 v[146:149], v34 offset:3072
	v_add_u32_e32 v34, s79, v242
	ds_read_b128 v[150:153], v34
	ds_read_b128 v[154:157], v34 offset:1024
	ds_read_b128 v[158:161], v34 offset:2048
	ds_read_b128 v[162:165], v34 offset:3072
	s_add_u32 s42, s42, 0x80000
	s_addc_u32 s43, s43, 0
	s_mov_b32 m0, s63
	v_lshl_add_u64 v[40:41], s[42:43], 0, v[208:209]
	ds_read_b128 v[166:169], v244 offset:32768
	ds_read_b128 v[170:173], v244 offset:33792
	ds_read_b128 v[174:177], v244 offset:34816
	ds_read_b128 v[178:181], v244 offset:35840
	ds_read_b128 v[182:185], v244 offset:36864
	ds_read_b128 v[186:189], v244 offset:37888
	ds_read_b128 v[190:193], v244 offset:38912
	ds_read_b128 v[194:197], v244 offset:39936
	global_load_lds_dwordx4 v[40:41], off
	v_lshl_add_u64 v[40:41], s[42:43], 0, v[212:213]
	s_mov_b32 m0, s64
	s_nop 0
	global_load_lds_dwordx4 v[40:41], off
	s_waitcnt vmcnt(8)
	s_waitcnt lgkmcnt(0)
	s_setprio 1
	s_barrier
	v_mfma_f32_16x16x32_bf16 v[130:133], v[134:137], v[166:169], v[130:133]
	v_mfma_f32_16x16x32_bf16 v[130:133], v[138:141], v[170:173], v[130:133]
	v_mfma_f32_16x16x32_bf16 v[126:129], v[142:145], v[166:169], v[126:129]
	v_mfma_f32_16x16x32_bf16 v[126:129], v[146:149], v[170:173], v[126:129]
	v_mfma_f32_16x16x32_bf16 v[114:117], v[134:137], v[174:177], v[114:117]
	v_mfma_f32_16x16x32_bf16 v[114:117], v[138:141], v[178:181], v[114:117]
	v_mfma_f32_16x16x32_bf16 v[110:113], v[142:145], v[174:177], v[110:113]
	v_mfma_f32_16x16x32_bf16 v[110:113], v[146:149], v[178:181], v[110:113]
	v_mfma_f32_16x16x32_bf16 v[98:101], v[134:137], v[182:185], v[98:101]
	v_mfma_f32_16x16x32_bf16 v[98:101], v[138:141], v[186:189], v[98:101]
	v_mfma_f32_16x16x32_bf16 v[94:97], v[142:145], v[182:185], v[94:97]
	v_mfma_f32_16x16x32_bf16 v[94:97], v[146:149], v[186:189], v[94:97]
	v_mfma_f32_16x16x32_bf16 v[82:85], v[134:137], v[190:193], v[82:85]
	v_mfma_f32_16x16x32_bf16 v[82:85], v[138:141], v[194:197], v[82:85]
	v_mfma_f32_16x16x32_bf16 v[78:81], v[142:145], v[190:193], v[78:81]
	v_mfma_f32_16x16x32_bf16 v[78:81], v[146:149], v[194:197], v[78:81]
	v_mfma_f32_16x16x32_bf16 v[122:125], v[150:153], v[166:169], v[122:125]
	v_mfma_f32_16x16x32_bf16 v[122:125], v[154:157], v[170:173], v[122:125]
	v_mfma_f32_16x16x32_bf16 v[118:121], v[158:161], v[166:169], v[118:121]
	v_mfma_f32_16x16x32_bf16 v[118:121], v[162:165], v[170:173], v[118:121]
	v_mfma_f32_16x16x32_bf16 v[106:109], v[150:153], v[174:177], v[106:109]
	v_mfma_f32_16x16x32_bf16 v[106:109], v[154:157], v[178:181], v[106:109]
	v_mfma_f32_16x16x32_bf16 v[102:105], v[158:161], v[174:177], v[102:105]
	v_mfma_f32_16x16x32_bf16 v[102:105], v[162:165], v[178:181], v[102:105]
	v_mfma_f32_16x16x32_bf16 v[90:93], v[150:153], v[182:185], v[90:93]
	v_mfma_f32_16x16x32_bf16 v[90:93], v[154:157], v[186:189], v[90:93]
	v_mfma_f32_16x16x32_bf16 v[86:89], v[158:161], v[182:185], v[86:89]
	v_mfma_f32_16x16x32_bf16 v[86:89], v[162:165], v[186:189], v[86:89]
	v_mfma_f32_16x16x32_bf16 v[74:77], v[150:153], v[190:193], v[74:77]
	v_mfma_f32_16x16x32_bf16 v[74:77], v[154:157], v[194:197], v[74:77]
	v_mfma_f32_16x16x32_bf16 v[70:73], v[158:161], v[190:193], v[70:73]
	v_mfma_f32_16x16x32_bf16 v[70:73], v[162:165], v[194:197], v[70:73]
	s_barrier
	s_setprio 0
	s_add_i32 s42, s78, s52
	v_lshl_add_u64 v[40:41], v[198:199], 0, s[18:19]
	s_mov_b32 m0, s42
	ds_read_b128 v[166:169], v244 offset:49152
	ds_read_b128 v[170:173], v244 offset:50176
	ds_read_b128 v[174:177], v244 offset:51200
	ds_read_b128 v[178:181], v244 offset:52224
	ds_read_b128 v[182:185], v244 offset:53248
	ds_read_b128 v[186:189], v244 offset:54272
	ds_read_b128 v[190:193], v244 offset:55296
	ds_read_b128 v[194:197], v244 offset:56320
	global_load_lds_dwordx4 v[40:41], off
	s_add_i32 m0, s42, 0x2000
	s_add_u32 s40, s40, 0x80080
	v_lshl_add_u64 v[40:41], v[200:201], 0, s[18:19]
	s_addc_u32 s41, s41, 0
	s_add_i32 s42, s79, s52
	global_load_lds_dwordx4 v[40:41], off
	v_lshl_add_u64 v[40:41], s[40:41], 0, v[210:211]
	s_mov_b32 m0, s42
	s_nop 0
	global_load_lds_dwordx4 v[40:41], off
	v_lshl_add_u64 v[40:41], s[40:41], 0, v[214:215]
	s_add_i32 m0, s42, 0x2000
	s_nop 0
	global_load_lds_dwordx4 v[40:41], off
	v_lshl_add_u64 v[40:41], v[246:247], 0, s[18:19]
	s_mov_b32 m0, s65
	s_nop 0
	global_load_lds_dwordx4 v[40:41], off
	v_lshl_add_u64 v[40:41], v[248:249], 0, s[18:19]
	s_mov_b32 m0, s66
	s_nop 0
	global_load_lds_dwordx4 v[40:41], off
	s_waitcnt vmcnt(8)
	s_waitcnt lgkmcnt(0)
	s_setprio 1
	s_barrier
	v_mfma_f32_16x16x32_bf16 v[66:69], v[134:137], v[166:169], v[66:69]
	v_mfma_f32_16x16x32_bf16 v[66:69], v[138:141], v[170:173], v[66:69]
	v_mfma_f32_16x16x32_bf16 v[62:65], v[142:145], v[166:169], v[62:65]
	v_mfma_f32_16x16x32_bf16 v[62:65], v[146:149], v[170:173], v[62:65]
	v_mfma_f32_16x16x32_bf16 v[50:53], v[134:137], v[174:177], v[50:53]
	v_mfma_f32_16x16x32_bf16 v[50:53], v[138:141], v[178:181], v[50:53]
	v_mfma_f32_16x16x32_bf16 v[46:49], v[142:145], v[174:177], v[46:49]
	v_mfma_f32_16x16x32_bf16 v[46:49], v[146:149], v[178:181], v[46:49]
	v_mfma_f32_16x16x32_bf16 v[30:33], v[134:137], v[182:185], v[30:33]
	v_mfma_f32_16x16x32_bf16 v[30:33], v[138:141], v[186:189], v[30:33]
	v_mfma_f32_16x16x32_bf16 v[26:29], v[142:145], v[182:185], v[26:29]
	v_mfma_f32_16x16x32_bf16 v[26:29], v[146:149], v[186:189], v[26:29]
	v_mfma_f32_16x16x32_bf16 v[14:17], v[134:137], v[190:193], v[14:17]
	v_mfma_f32_16x16x32_bf16 v[14:17], v[138:141], v[194:197], v[14:17]
	v_mfma_f32_16x16x32_bf16 v[10:13], v[142:145], v[190:193], v[10:13]
	v_mfma_f32_16x16x32_bf16 v[10:13], v[146:149], v[194:197], v[10:13]
	v_mfma_f32_16x16x32_bf16 v[58:61], v[150:153], v[166:169], v[58:61]
	v_mfma_f32_16x16x32_bf16 v[58:61], v[154:157], v[170:173], v[58:61]
	v_mfma_f32_16x16x32_bf16 v[54:57], v[158:161], v[166:169], v[54:57]
	v_mfma_f32_16x16x32_bf16 v[54:57], v[162:165], v[170:173], v[54:57]
	v_mfma_f32_16x16x32_bf16 v[40:43], v[150:153], v[174:177], v[42:45]
	v_mfma_f32_16x16x32_bf16 v[42:45], v[154:157], v[178:181], v[40:43]
	v_mfma_f32_16x16x32_bf16 v[36:39], v[158:161], v[174:177], v[36:39]
	v_mfma_f32_16x16x32_bf16 v[38:41], v[162:165], v[178:181], v[36:39]
	v_mfma_f32_16x16x32_bf16 v[22:25], v[150:153], v[182:185], v[22:25]
	v_mfma_f32_16x16x32_bf16 v[22:25], v[154:157], v[186:189], v[22:25]
	v_mfma_f32_16x16x32_bf16 v[18:21], v[158:161], v[182:185], v[18:21]
	v_mfma_f32_16x16x32_bf16 v[18:21], v[162:165], v[186:189], v[18:21]
	v_mfma_f32_16x16x32_bf16 v[6:9], v[150:153], v[190:193], v[6:9]
	v_mfma_f32_16x16x32_bf16 v[6:9], v[154:157], v[194:197], v[6:9]
	v_mfma_f32_16x16x32_bf16 v[2:5], v[158:161], v[190:193], v[2:5]
	v_mfma_f32_16x16x32_bf16 v[2:5], v[162:165], v[194:197], v[2:5]
	s_barrier
	s_setprio 0
	s_add_i32 vcc_lo, vcc_lo, 2
	s_add_u32 s36, s36, 0x100
	s_addc_u32 s37, s37, 0
	s_cmp_gt_u32 vcc_lo, 29
	s_cbranch_scc1 .LBB0_1648

.LBB0_1646:
	v_add_u32_e32 v34, 0, v242
	v_add_u32_e32 v36, 0x10000, v34
	v_add_u32_e32 v34, 0x14000, v34
	ds_read_b128 v[150:153], v36
	ds_read_b128 v[154:157], v36 offset:1024
	ds_read_b128 v[158:161], v36 offset:2048
	ds_read_b128 v[162:165], v36 offset:3072
	ds_read_b128 v[134:137], v34
	ds_read_b128 v[138:141], v34 offset:1024
	ds_read_b128 v[142:145], v34 offset:2048
	ds_read_b128 v[146:149], v34 offset:3072
	v_lshl_add_u64 v[36:37], v[224:225], 0, s[36:37]
	s_add_i32 m0, s54, 0xc000
	ds_read_b128 v[190:193], v244
	ds_read_b128 v[194:197], v244 offset:1024
	ds_read_b128 v[182:185], v244 offset:2048
	ds_read_b128 v[186:189], v244 offset:3072
	ds_read_b128 v[174:177], v244 offset:4096
	ds_read_b128 v[178:181], v244 offset:5120
	ds_read_b128 v[166:169], v244 offset:6144
	ds_read_b128 v[170:173], v244 offset:7168
	global_load_lds_dwordx4 v[36:37], off
	v_lshl_add_u64 v[36:37], v[226:227], 0, s[36:37]
	s_add_i32 m0, s54, 0xe000
	s_cmp_lg_u32 s36, 0
	global_load_lds_dwordx4 v[36:37], off
	s_waitcnt vmcnt(8)
	s_waitcnt lgkmcnt(0)
	s_add_u32 s40, s34, s36
	s_addc_u32 s41, s35, s37
	s_add_u32 s40, s40, 0x100
	s_addc_u32 s41, s41, 0
	s_add_u32 s78, s31, s36
	s_addc_u32 s79, s77, s37
	s_cmpk_eq_i32 s36, 0xf00
	s_cselect_b32 s43, s13, s41
	s_cselect_b32 s42, s23, s40
	s_cselect_b32 s41, s21, s79
	s_cselect_b32 s40, s76, s78
	s_cmp_lg_u32 s36, 0
	s_setprio 1
	s_barrier
	s_cbranch_scc1 .LBB0_1643
	s_add_i32 m0, s54, 0x21200
	s_nop 0
	global_load_lds_dwordx4 v[222:223], off
	s_branch .LBB0_1643
